# GEMM main loops: per-segment s_setprio flips replaced by one static s_setprio 1 for waves 4-7
# speedup vs baseline: 1.0708x; 1.0079x over previous
.LBB0_18:
	s_andn2_b64 vcc, exec, s[0:1]
	s_cbranch_vccnz .LBB0_177
	s_cmp_eq_u32 s17, 10
	s_cbranch_scc0 .LBB0_177
	v_readlane_b32 s0, v250, 6
	v_readlane_b32 s1, v250, 7
	s_andn2_b64 vcc, exec, s[0:1]
	v_readfirstlane_b32 s36, v166
	s_cbranch_vccnz .LBB0_177
	v_lshlrev_b32_e32 v0, 4, v166
	s_waitcnt vmcnt(0)
	v_add_u32_e32 v4, 0x2000, v0
	v_ashrrev_i32_e32 v2, 31, v4
	v_lshrrev_b32_e32 v2, 22, v2
	v_add_u32_e32 v2, v4, v2
	v_ashrrev_i32_e32 v3, 10, v2
	v_mul_i32_i24_e32 v5, 0x400, v3
	v_sub_u32_e32 v4, v4, v5
	v_lshrrev_b32_e32 v5, 4, v4
	v_bitop3_b32 v4, v5, v4, 32 bitop3:0x6c
	v_ashrrev_i32_e32 v5, 31, v4
	v_bfe_i32 v8, v166, 27, 1
	v_lshrrev_b32_e32 v5, 26, v5
	v_lshrrev_b32_e32 v8, 22, v8
	v_add_u32_e32 v6, v4, v5
	v_add_u32_e32 v8, v0, v8
	v_ashrrev_i32_e32 v5, 6, v6
	v_and_b32_e32 v6, 0xc0, v6
	v_and_b32_e32 v8, 0xfffffc00, v8
	v_sub_u32_e32 v4, v4, v6
	v_lshlrev_b32_e32 v6, 3, v3
	v_sub_u32_e32 v0, v0, v8
	v_and_b32_e32 v6, 0x7ffff0, v6
	v_lshrrev_b32_e32 v8, 4, v0
	v_lshlrev_b32_e32 v2, 5, v3
	v_ashrrev_i16_sdwa v4, v203, sext(v4) dst_sel:DWORD dst_unused:UNUSED_PAD src0_sel:DWORD src1_sel:BYTE_0
	v_add_u32_e32 v6, v5, v6
	s_movk_i32 s1, 0x1600
	v_bitop3_b32 v0, v8, v0, 32 bitop3:0x6c
	v_and_b32_e32 v2, 32, v2
	v_bfe_i32 v4, v4, 0, 16
	v_mul_lo_u32 v6, v6, s1
	v_ashrrev_i32_e32 v8, 31, v0
	v_add3_u32 v7, v2, v4, v6
	v_lshrrev_b32_e32 v8, 26, v8
	v_add_lshl_u32 v132, v7, v6, 1
	v_ashrrev_i32_e32 v6, 31, v166
	v_add_u32_e32 v8, v0, v8
	v_lshrrev_b32_e32 v6, 26, v6
	v_ashrrev_i32_e32 v9, 6, v8
	v_and_b32_e32 v8, 0xc0, v8
	v_add_u32_e32 v6, v166, v6
	v_sub_u32_e32 v0, v0, v8
	v_lshlrev_b32_e32 v130, 1, v7
	v_ashrrev_i32_e32 v7, 6, v6
	v_ashrrev_i16_sdwa v0, v203, sext(v0) dst_sel:DWORD dst_unused:UNUSED_PAD src0_sel:DWORD src1_sel:BYTE_0
	v_bfe_i32 v8, v0, 0, 16
	v_lshlrev_b32_e32 v0, 3, v7
	v_and_b32_e32 v0, 0x7ffff0, v0
	s_ashr_i32 s0, s36, 6
	v_lshlrev_b32_e32 v6, 5, v7
	v_add_u32_e32 v0, v9, v0
	s_lshl_b32 s52, s0, 10
	v_and_b32_e32 v6, 32, v6
	v_mul_lo_u32 v10, v0, s1
	v_add3_u32 v11, v6, v8, v10
	s_add_i32 s53, s52, 0
	v_readlane_b32 s12, v252, 62
	v_lshlrev_b32_e32 v0, 1, v11
	s_add_i32 m0, s53, 0x10000
	v_readlane_b32 s13, v252, 63
	v_add_lshl_u32 v134, v11, v10, 1
	s_add_i32 s54, s53, 0x2000
	s_add_i32 s55, s53, 0x4000
	s_add_i32 s56, s53, 0x6000
	s_ashr_i32 s1, s36, 8
	global_load_lds_dwordx4 v0, s[12:13]
	s_add_i32 m0, s53, 0x12000
	s_nop 0
	global_load_lds_dwordx4 v130, s[12:13]
	v_readlane_b32 s12, v252, 58
	s_mov_b32 m0, s53
	v_readlane_b32 s13, v252, 59
	s_nop 4
	global_load_lds_dwordx4 v134, s[12:13]
	s_mov_b32 m0, s54
	s_nop 0
	global_load_lds_dwordx4 v132, s[12:13]
	v_readlane_b32 s12, v252, 56
	s_add_i32 m0, s53, 0x14000
	v_readlane_b32 s13, v252, 57
	s_nop 4
	global_load_lds_dwordx4 v0, s[12:13]
	s_add_i32 m0, s53, 0x16000
	s_cmp_lg_u32 s1, 1
	global_load_lds_dwordx4 v130, s[12:13]
	v_readlane_b32 s12, v252, 60
	s_mov_b32 m0, s55
	v_readlane_b32 s13, v252, 61
	s_nop 4
	global_load_lds_dwordx4 v134, s[12:13]
	s_mov_b32 m0, s56
	s_nop 0
	global_load_lds_dwordx4 v132, s[12:13]
	s_cbranch_scc1 .LBB0_23
	s_barrier
	s_setprio 1

.LBB0_37:
	s_add_i32 s69, s48, 2
	s_add_u32 s46, s0, 0x100
	s_addc_u32 s47, s1, 0
	s_add_i32 s70, 0, 0x10000
	v_add_u32_e32 v156, s70, v153
	ds_read_b128 v[140:143], v156
	ds_read_b128 v[144:147], v156 offset:1024
	ds_read_b128 v[148:151], v156 offset:2048
	ds_read_b128 v[168:171], v156 offset:3072
	s_cmp_eq_u32 s12, s48
	s_cselect_b32 s48, s44, s13
	s_cselect_b32 s51, s43, s47
	s_cselect_b32 s50, s42, s46
	s_cselect_b32 s49, s45, s68
	v_lshl_add_u64 v[156:157], s[0:1], 0, v[136:137]
	s_add_i32 m0, s53, 0xc000
	ds_read_b128 v[172:175], v155
	ds_read_b128 v[176:179], v155 offset:1024
	ds_read_b128 v[180:183], v155 offset:2048
	ds_read_b128 v[184:187], v155 offset:3072
	ds_read_b128 v[188:191], v155 offset:4096
	ds_read_b128 v[192:195], v155 offset:5120
	ds_read_b128 v[196:199], v155 offset:6144
	ds_read_b128 v[224:227], v155 offset:7168
	global_load_lds_dwordx4 v[156:157], off
	v_lshl_add_u64 v[156:157], s[0:1], 0, v[138:139]
	s_add_i32 m0, s53, 0xe000
	s_nop 0
	global_load_lds_dwordx4 v[156:157], off
	s_waitcnt lgkmcnt(8)
	s_barrier
	s_waitcnt lgkmcnt(0)
	s_waitcnt lgkmcnt(0)
	v_mfma_f32_16x16x32_bf16 v[126:129], v[140:143], v[172:175], v[126:129]
	v_mfma_f32_16x16x32_bf16 v[122:125], v[148:151], v[172:175], v[122:125]
	v_mfma_f32_16x16x32_bf16 v[110:113], v[140:143], v[180:183], v[110:113]
	v_mfma_f32_16x16x32_bf16 v[106:109], v[148:151], v[180:183], v[106:109]
	v_mfma_f32_16x16x32_bf16 v[94:97], v[140:143], v[188:191], v[94:97]
	v_mfma_f32_16x16x32_bf16 v[90:93], v[148:151], v[188:191], v[90:93]
	v_mfma_f32_16x16x32_bf16 v[78:81], v[140:143], v[196:199], v[78:81]
	v_mfma_f32_16x16x32_bf16 v[74:77], v[148:151], v[196:199], v[74:77]
	v_mfma_f32_16x16x32_bf16 v[126:129], v[144:147], v[176:179], v[126:129]
	v_mfma_f32_16x16x32_bf16 v[122:125], v[168:171], v[176:179], v[122:125]
	v_mfma_f32_16x16x32_bf16 v[110:113], v[144:147], v[184:187], v[110:113]
	v_mfma_f32_16x16x32_bf16 v[106:109], v[168:171], v[184:187], v[106:109]
	v_mfma_f32_16x16x32_bf16 v[94:97], v[144:147], v[192:195], v[94:97]
	v_mfma_f32_16x16x32_bf16 v[90:93], v[168:171], v[192:195], v[90:93]
	v_mfma_f32_16x16x32_bf16 v[78:81], v[144:147], v[224:227], v[78:81]
	v_mfma_f32_16x16x32_bf16 v[74:77], v[168:171], v[224:227], v[74:77]
	s_barrier
	s_add_i32 s71, 0, 0x14000
	v_add_u32_e32 v156, s71, v153
	s_add_i32 s0, s70, s52
	ds_read_b128 v[228:231], v156
	ds_read_b128 v[232:235], v156 offset:1024
	ds_read_b128 v[236:239], v156 offset:2048
	ds_read_b128 v[240:243], v156 offset:3072
	v_lshl_add_u64 v[156:157], s[48:49], 0, v[0:1]
	s_mov_b32 m0, s0
	v_lshl_add_u64 v[200:201], s[48:49], 0, v[130:131]
	global_load_lds_dwordx4 v[156:157], off
	s_add_i32 m0, s0, 0x2000
	s_nop 0
	global_load_lds_dwordx4 v[200:201], off
	s_barrier
	s_waitcnt lgkmcnt(0)
	s_waitcnt lgkmcnt(0)
	v_mfma_f32_16x16x32_bf16 v[118:121], v[228:231], v[172:175], v[118:121]
	v_mfma_f32_16x16x32_bf16 v[114:117], v[236:239], v[172:175], v[114:117]
	v_mfma_f32_16x16x32_bf16 v[102:105], v[228:231], v[180:183], v[102:105]
	v_mfma_f32_16x16x32_bf16 v[98:101], v[236:239], v[180:183], v[98:101]
	v_mfma_f32_16x16x32_bf16 v[86:89], v[228:231], v[188:191], v[86:89]
	v_mfma_f32_16x16x32_bf16 v[82:85], v[236:239], v[188:191], v[82:85]
	v_mfma_f32_16x16x32_bf16 v[70:73], v[228:231], v[196:199], v[70:73]
	v_mfma_f32_16x16x32_bf16 v[66:69], v[236:239], v[196:199], v[66:69]
	v_mfma_f32_16x16x32_bf16 v[118:121], v[232:235], v[176:179], v[118:121]
	v_mfma_f32_16x16x32_bf16 v[114:117], v[240:243], v[176:179], v[114:117]
	v_mfma_f32_16x16x32_bf16 v[102:105], v[232:235], v[184:187], v[102:105]
	v_mfma_f32_16x16x32_bf16 v[98:101], v[240:243], v[184:187], v[98:101]
	v_mfma_f32_16x16x32_bf16 v[86:89], v[232:235], v[192:195], v[86:89]
	v_mfma_f32_16x16x32_bf16 v[82:85], v[240:243], v[192:195], v[82:85]
	v_mfma_f32_16x16x32_bf16 v[70:73], v[232:235], v[224:227], v[70:73]
	v_mfma_f32_16x16x32_bf16 v[66:69], v[240:243], v[224:227], v[66:69]
	s_mov_b32 m0, s53
	v_lshl_add_u64 v[210:211], s[50:51], 0, v[134:135]
	s_barrier
	ds_read_b128 v[172:175], v155 offset:16384
	ds_read_b128 v[176:179], v155 offset:17408
	ds_read_b128 v[180:183], v155 offset:18432
	ds_read_b128 v[184:187], v155 offset:19456
	ds_read_b128 v[188:191], v155 offset:20480
	ds_read_b128 v[192:195], v155 offset:21504
	ds_read_b128 v[196:199], v155 offset:22528
	ds_read_b128 v[224:227], v155 offset:23552
	global_load_lds_dwordx4 v[210:211], off
	v_lshl_add_u64 v[212:213], s[50:51], 0, v[132:133]
	s_mov_b32 m0, s54
	s_nop 0
	global_load_lds_dwordx4 v[212:213], off
	s_barrier
	s_waitcnt lgkmcnt(0)
	s_waitcnt lgkmcnt(0)
	v_mfma_f32_16x16x32_bf16 v[62:65], v[140:143], v[172:175], v[62:65]
	v_mfma_f32_16x16x32_bf16 v[58:61], v[148:151], v[172:175], v[58:61]
	v_mfma_f32_16x16x32_bf16 v[46:49], v[140:143], v[180:183], v[46:49]
	v_mfma_f32_16x16x32_bf16 v[42:45], v[148:151], v[180:183], v[42:45]
	v_mfma_f32_16x16x32_bf16 v[30:33], v[140:143], v[188:191], v[30:33]
	v_mfma_f32_16x16x32_bf16 v[26:29], v[148:151], v[188:191], v[26:29]
	v_mfma_f32_16x16x32_bf16 v[14:17], v[140:143], v[196:199], v[14:17]
	v_mfma_f32_16x16x32_bf16 v[10:13], v[148:151], v[196:199], v[10:13]
	v_mfma_f32_16x16x32_bf16 v[62:65], v[144:147], v[176:179], v[62:65]
	v_mfma_f32_16x16x32_bf16 v[58:61], v[168:171], v[176:179], v[58:61]
	v_mfma_f32_16x16x32_bf16 v[46:49], v[144:147], v[184:187], v[46:49]
	v_mfma_f32_16x16x32_bf16 v[42:45], v[168:171], v[184:187], v[42:45]
	v_mfma_f32_16x16x32_bf16 v[30:33], v[144:147], v[192:195], v[30:33]
	v_mfma_f32_16x16x32_bf16 v[26:29], v[168:171], v[192:195], v[26:29]
	v_mfma_f32_16x16x32_bf16 v[14:17], v[144:147], v[224:227], v[14:17]
	v_mfma_f32_16x16x32_bf16 v[10:13], v[168:171], v[224:227], v[10:13]
	s_barrier
	s_add_u32 s0, s48, 0x160000
	s_addc_u32 s1, s49, 0
	s_add_i32 s70, s71, s52
	v_lshl_add_u64 v[140:141], s[0:1], 0, v[0:1]
	s_mov_b32 m0, s70
	s_nop 0
	global_load_lds_dwordx4 v[140:141], off
	v_lshl_add_u64 v[140:141], s[0:1], 0, v[130:131]
	s_add_i32 m0, s70, 0x2000
	s_nop 0
	global_load_lds_dwordx4 v[140:141], off
	s_waitcnt vmcnt(6)
	s_barrier
	v_mfma_f32_16x16x32_bf16 v[54:57], v[228:231], v[172:175], v[54:57]
	v_mfma_f32_16x16x32_bf16 v[50:53], v[236:239], v[172:175], v[50:53]
	v_mfma_f32_16x16x32_bf16 v[38:41], v[228:231], v[180:183], v[38:41]
	v_mfma_f32_16x16x32_bf16 v[34:37], v[236:239], v[180:183], v[34:37]
	v_mfma_f32_16x16x32_bf16 v[22:25], v[228:231], v[188:191], v[22:25]
	v_mfma_f32_16x16x32_bf16 v[18:21], v[236:239], v[188:191], v[18:21]
	v_mfma_f32_16x16x32_bf16 v[6:9], v[228:231], v[196:199], v[6:9]
	v_mfma_f32_16x16x32_bf16 v[2:5], v[236:239], v[196:199], v[2:5]
	v_mfma_f32_16x16x32_bf16 v[54:57], v[232:235], v[176:179], v[54:57]
	v_mfma_f32_16x16x32_bf16 v[50:53], v[240:243], v[176:179], v[50:53]
	v_mfma_f32_16x16x32_bf16 v[38:41], v[232:235], v[184:187], v[38:41]
	v_mfma_f32_16x16x32_bf16 v[34:37], v[240:243], v[184:187], v[34:37]
	v_mfma_f32_16x16x32_bf16 v[22:25], v[232:235], v[192:195], v[22:25]
	v_mfma_f32_16x16x32_bf16 v[18:21], v[240:243], v[192:195], v[18:21]
	v_mfma_f32_16x16x32_bf16 v[6:9], v[232:235], v[224:227], v[6:9]
	v_mfma_f32_16x16x32_bf16 v[2:5], v[240:243], v[224:227], v[2:5]
	s_add_i32 s70, 0, 0x18000
	v_add_u32_e32 v161, s70, v153
	s_barrier
	ds_read_b128 v[140:143], v161
	ds_read_b128 v[144:147], v161 offset:1024
	ds_read_b128 v[148:151], v161 offset:2048
	ds_read_b128 v[168:171], v161 offset:3072
	s_add_u32 s0, s50, 0x2c0000
	s_addc_u32 s1, s51, 0
	s_mov_b32 m0, s55
	v_lshl_add_u64 v[220:221], s[0:1], 0, v[134:135]
	ds_read_b128 v[172:175], v155 offset:32768
	ds_read_b128 v[176:179], v155 offset:33792
	ds_read_b128 v[180:183], v155 offset:34816
	ds_read_b128 v[184:187], v155 offset:35840
	ds_read_b128 v[188:191], v155 offset:36864
	ds_read_b128 v[192:195], v155 offset:37888
	ds_read_b128 v[196:199], v155 offset:38912
	ds_read_b128 v[224:227], v155 offset:39936
	global_load_lds_dwordx4 v[220:221], off
	v_lshl_add_u64 v[220:221], s[0:1], 0, v[132:133]
	s_mov_b32 m0, s56
	s_nop 0
	global_load_lds_dwordx4 v[220:221], off
	s_waitcnt lgkmcnt(8)
	s_barrier
	s_waitcnt lgkmcnt(0)
	s_waitcnt lgkmcnt(0)
	v_mfma_f32_16x16x32_bf16 v[126:129], v[140:143], v[172:175], v[126:129]
	v_mfma_f32_16x16x32_bf16 v[122:125], v[148:151], v[172:175], v[122:125]
	v_mfma_f32_16x16x32_bf16 v[110:113], v[140:143], v[180:183], v[110:113]
	v_mfma_f32_16x16x32_bf16 v[106:109], v[148:151], v[180:183], v[106:109]
	v_mfma_f32_16x16x32_bf16 v[94:97], v[140:143], v[188:191], v[94:97]
	v_mfma_f32_16x16x32_bf16 v[90:93], v[148:151], v[188:191], v[90:93]
	v_mfma_f32_16x16x32_bf16 v[78:81], v[140:143], v[196:199], v[78:81]
	v_mfma_f32_16x16x32_bf16 v[74:77], v[148:151], v[196:199], v[74:77]
	v_mfma_f32_16x16x32_bf16 v[126:129], v[144:147], v[176:179], v[126:129]
	v_mfma_f32_16x16x32_bf16 v[122:125], v[168:171], v[176:179], v[122:125]
	v_mfma_f32_16x16x32_bf16 v[110:113], v[144:147], v[184:187], v[110:113]
	v_mfma_f32_16x16x32_bf16 v[106:109], v[168:171], v[184:187], v[106:109]
	v_mfma_f32_16x16x32_bf16 v[94:97], v[144:147], v[192:195], v[94:97]
	v_mfma_f32_16x16x32_bf16 v[90:93], v[168:171], v[192:195], v[90:93]
	v_mfma_f32_16x16x32_bf16 v[78:81], v[144:147], v[224:227], v[78:81]
	v_mfma_f32_16x16x32_bf16 v[74:77], v[168:171], v[224:227], v[74:77]
	s_barrier
	s_add_i32 s50, 0, 0x1c000
	s_add_i32 s0, s70, s52
	v_add_u32_e32 v161, s50, v153
	v_lshl_add_u64 v[156:157], v[156:157], 0, s[94:95]
	s_mov_b32 m0, s0
	ds_read_b128 v[228:231], v161
	ds_read_b128 v[232:235], v161 offset:1024
	ds_read_b128 v[236:239], v161 offset:2048
	ds_read_b128 v[240:243], v161 offset:3072
	global_load_lds_dwordx4 v[156:157], off
	v_lshl_add_u64 v[156:157], v[200:201], 0, s[94:95]
	s_add_i32 m0, s0, 0x2000
	s_nop 0
	global_load_lds_dwordx4 v[156:157], off
	s_barrier
	s_waitcnt lgkmcnt(0)
	s_waitcnt lgkmcnt(0)
	v_mfma_f32_16x16x32_bf16 v[118:121], v[228:231], v[172:175], v[118:121]
	v_mfma_f32_16x16x32_bf16 v[114:117], v[236:239], v[172:175], v[114:117]
	v_mfma_f32_16x16x32_bf16 v[102:105], v[228:231], v[180:183], v[102:105]
	v_mfma_f32_16x16x32_bf16 v[98:101], v[236:239], v[180:183], v[98:101]
	v_mfma_f32_16x16x32_bf16 v[86:89], v[228:231], v[188:191], v[86:89]
	v_mfma_f32_16x16x32_bf16 v[82:85], v[236:239], v[188:191], v[82:85]
	v_mfma_f32_16x16x32_bf16 v[70:73], v[228:231], v[196:199], v[70:73]
	v_mfma_f32_16x16x32_bf16 v[66:69], v[236:239], v[196:199], v[66:69]
	v_mfma_f32_16x16x32_bf16 v[118:121], v[232:235], v[176:179], v[118:121]
	v_mfma_f32_16x16x32_bf16 v[114:117], v[240:243], v[176:179], v[114:117]
	v_mfma_f32_16x16x32_bf16 v[102:105], v[232:235], v[184:187], v[102:105]
	v_mfma_f32_16x16x32_bf16 v[98:101], v[240:243], v[184:187], v[98:101]
	v_mfma_f32_16x16x32_bf16 v[86:89], v[232:235], v[192:195], v[86:89]
	v_mfma_f32_16x16x32_bf16 v[82:85], v[240:243], v[192:195], v[82:85]
	v_mfma_f32_16x16x32_bf16 v[70:73], v[232:235], v[224:227], v[70:73]
	v_mfma_f32_16x16x32_bf16 v[66:69], v[240:243], v[224:227], v[66:69]
	s_mov_b32 m0, s57
	v_lshl_add_u64 v[156:157], v[210:211], 0, s[94:95]
	s_barrier
	ds_read_b128 v[172:175], v155 offset:49152
	ds_read_b128 v[176:179], v155 offset:50176
	ds_read_b128 v[180:183], v155 offset:51200
	ds_read_b128 v[184:187], v155 offset:52224
	ds_read_b128 v[188:191], v155 offset:53248
	ds_read_b128 v[192:195], v155 offset:54272
	ds_read_b128 v[196:199], v155 offset:55296
	ds_read_b128 v[224:227], v155 offset:56320
	global_load_lds_dwordx4 v[156:157], off
	v_lshl_add_u64 v[156:157], v[212:213], 0, s[94:95]
	s_mov_b32 m0, s58
	s_nop 0
	global_load_lds_dwordx4 v[156:157], off
	s_barrier
	s_waitcnt lgkmcnt(0)
	s_waitcnt lgkmcnt(0)
	v_mfma_f32_16x16x32_bf16 v[62:65], v[140:143], v[172:175], v[62:65]
	v_mfma_f32_16x16x32_bf16 v[58:61], v[148:151], v[172:175], v[58:61]
	v_mfma_f32_16x16x32_bf16 v[46:49], v[140:143], v[180:183], v[46:49]
	v_mfma_f32_16x16x32_bf16 v[42:45], v[148:151], v[180:183], v[42:45]
	v_mfma_f32_16x16x32_bf16 v[30:33], v[140:143], v[188:191], v[30:33]
	v_mfma_f32_16x16x32_bf16 v[26:29], v[148:151], v[188:191], v[26:29]
	v_mfma_f32_16x16x32_bf16 v[14:17], v[140:143], v[196:199], v[14:17]
	v_mfma_f32_16x16x32_bf16 v[10:13], v[148:151], v[196:199], v[10:13]
	v_mfma_f32_16x16x32_bf16 v[62:65], v[144:147], v[176:179], v[62:65]
	v_mfma_f32_16x16x32_bf16 v[58:61], v[168:171], v[176:179], v[58:61]
	v_mfma_f32_16x16x32_bf16 v[46:49], v[144:147], v[184:187], v[46:49]
	v_mfma_f32_16x16x32_bf16 v[42:45], v[168:171], v[184:187], v[42:45]
	v_mfma_f32_16x16x32_bf16 v[30:33], v[144:147], v[192:195], v[30:33]
	v_mfma_f32_16x16x32_bf16 v[26:29], v[168:171], v[192:195], v[26:29]
	v_mfma_f32_16x16x32_bf16 v[14:17], v[144:147], v[224:227], v[14:17]
	v_mfma_f32_16x16x32_bf16 v[10:13], v[168:171], v[224:227], v[10:13]
	s_barrier
	s_add_u32 s0, s48, 0x160080
	s_addc_u32 s1, s49, 0
	s_add_i32 s48, s50, s52
	v_lshl_add_u64 v[140:141], s[0:1], 0, v[0:1]
	s_mov_b32 m0, s48
	s_nop 0
	global_load_lds_dwordx4 v[140:141], off
	v_lshl_add_u64 v[140:141], s[0:1], 0, v[130:131]
	s_add_i32 m0, s48, 0x2000
	s_nop 0
	global_load_lds_dwordx4 v[140:141], off
	s_waitcnt vmcnt(6)
	s_barrier
	v_mfma_f32_16x16x32_bf16 v[54:57], v[228:231], v[172:175], v[54:57]
	v_mfma_f32_16x16x32_bf16 v[50:53], v[236:239], v[172:175], v[50:53]
	v_mfma_f32_16x16x32_bf16 v[38:41], v[228:231], v[180:183], v[38:41]
	v_mfma_f32_16x16x32_bf16 v[34:37], v[236:239], v[180:183], v[34:37]
	v_mfma_f32_16x16x32_bf16 v[22:25], v[228:231], v[188:191], v[22:25]
	v_mfma_f32_16x16x32_bf16 v[18:21], v[236:239], v[188:191], v[18:21]
	v_mfma_f32_16x16x32_bf16 v[6:9], v[228:231], v[196:199], v[6:9]
	v_mfma_f32_16x16x32_bf16 v[2:5], v[236:239], v[196:199], v[2:5]
	v_mfma_f32_16x16x32_bf16 v[54:57], v[232:235], v[176:179], v[54:57]
	v_mfma_f32_16x16x32_bf16 v[50:53], v[240:243], v[176:179], v[50:53]
	v_mfma_f32_16x16x32_bf16 v[38:41], v[232:235], v[184:187], v[38:41]
	v_mfma_f32_16x16x32_bf16 v[34:37], v[240:243], v[184:187], v[34:37]
	v_mfma_f32_16x16x32_bf16 v[22:25], v[232:235], v[192:195], v[22:25]
	v_mfma_f32_16x16x32_bf16 v[18:21], v[240:243], v[192:195], v[18:21]
	v_mfma_f32_16x16x32_bf16 v[6:9], v[232:235], v[224:227], v[6:9]
	v_mfma_f32_16x16x32_bf16 v[2:5], v[240:243], v[224:227], v[2:5]
	s_add_u32 s13, s13, 0x100
	s_addc_u32 s68, s68, 0
	s_cmp_ge_i32 s69, s39
	s_mov_b64 s[0:1], s[46:47]
	s_mov_b32 s48, s69
	s_barrier
	s_cbranch_scc0 .LBB0_37
	s_cmp_eq_u32 s65, 2
	s_cbranch_scc1 .Lepi10_orig
	v_readlane_b32 s90, v255, 17
	v_readlane_b32 s91, v255, 18
	v_readlane_b32 s96, v255, 19
	v_readlane_b32 s97, v255, 20
	v_lshl_or_b32 v156, s66, 8, v154
	v_lshlrev_b32_e32 v156, 2, v156
	v_lshl_add_u32 v157, v152, 13, v156
	s_lshl_b32 s72, s67, 21
	s_add_u32 s74, s22, s72
	s_addc_u32 s75, s23, 0
	s_add_u32 s76, s22, s72
	s_addc_u32 s77, s23, 0
	s_lshr_b32 s73, s67, 3
	s_mul_i32 s73, s73, 0xc000
	s_add_u32 s73, s73, 0xa000
	s_add_u32 s70, s90, s73
	s_addc_u32 s71, s91, 0
	global_load_dwordx4 v[140:143], v156, s[70:71]
	global_load_dwordx4 v[144:147], v156, s[70:71] offset:64
	global_load_dwordx4 v[148:151], v156, s[70:71] offset:512
	global_load_dwordx4 v[168:171], v156, s[70:71] offset:576
	global_load_dwordx4 v[224:227], v157, s[74:75] nt
	global_load_dwordx4 v[228:231], v157, s[74:75] offset:64 nt
	global_load_dwordx4 v[232:235], v157, s[74:75] offset:512 nt
	global_load_dwordx4 v[236:239], v157, s[74:75] offset:576 nt
	s_add_u32 s74, s74, 0x20000
	s_addc_u32 s75, s75, 0
	global_load_dwordx4 v[240:243], v157, s[74:75] nt
	global_load_dwordx4 v[244:247], v157, s[74:75] offset:64 nt
	s_waitcnt vmcnt(5)
	v_pk_fma_f32 v[128:129], v[128:129], v[142:143], v[226:227]
	v_pk_fma_f32 v[126:127], v[126:127], v[140:141], v[224:225]
	global_store_dwordx4 v157, v[126:129], s[76:77] nt
	global_load_dwordx4 v[224:227], v157, s[74:75] offset:512 nt
	s_waitcnt vmcnt(6)
	v_pk_fma_f32 v[124:125], v[124:125], v[146:147], v[230:231]
	v_pk_fma_f32 v[122:123], v[122:123], v[144:145], v[228:229]
	global_store_dwordx4 v157, v[122:125], s[76:77] offset:64 nt
	global_load_dwordx4 v[228:231], v157, s[74:75] offset:576 nt
	s_waitcnt vmcnt(7)
	v_pk_fma_f32 v[120:121], v[120:121], v[150:151], v[234:235]
	v_pk_fma_f32 v[118:119], v[118:119], v[148:149], v[232:233]
	global_store_dwordx4 v157, v[118:121], s[76:77] offset:512 nt
	s_add_u32 s74, s74, 0x20000
	s_addc_u32 s75, s75, 0
	global_load_dwordx4 v[232:235], v157, s[74:75] nt
	s_waitcnt vmcnt(8)
	v_pk_fma_f32 v[116:117], v[116:117], v[170:171], v[238:239]
	v_pk_fma_f32 v[114:115], v[114:115], v[168:169], v[236:237]
	global_store_dwordx4 v157, v[114:117], s[76:77] offset:576 nt
	global_load_dwordx4 v[236:239], v157, s[74:75] offset:64 nt
	s_add_u32 s76, s76, 0x20000
	s_addc_u32 s77, s77, 0
	s_waitcnt vmcnt(9)
	v_pk_fma_f32 v[112:113], v[112:113], v[142:143], v[242:243]
	v_pk_fma_f32 v[110:111], v[110:111], v[140:141], v[240:241]
	global_store_dwordx4 v157, v[110:113], s[76:77] nt
	global_load_dwordx4 v[240:243], v157, s[74:75] offset:512 nt
	s_waitcnt vmcnt(10)
	v_pk_fma_f32 v[108:109], v[108:109], v[146:147], v[246:247]
	v_pk_fma_f32 v[106:107], v[106:107], v[144:145], v[244:245]
	global_store_dwordx4 v157, v[106:109], s[76:77] offset:64 nt
	global_load_dwordx4 v[244:247], v157, s[74:75] offset:576 nt
	s_waitcnt vmcnt(10)
	v_pk_fma_f32 v[104:105], v[104:105], v[150:151], v[226:227]
	v_pk_fma_f32 v[102:103], v[102:103], v[148:149], v[224:225]
	global_store_dwordx4 v157, v[102:105], s[76:77] offset:512 nt
	s_add_u32 s74, s74, 0x20000
	s_addc_u32 s75, s75, 0
	global_load_dwordx4 v[224:227], v157, s[74:75] nt
	s_waitcnt vmcnt(10)
	v_pk_fma_f32 v[100:101], v[100:101], v[170:171], v[230:231]
	v_pk_fma_f32 v[98:99], v[98:99], v[168:169], v[228:229]
	global_store_dwordx4 v157, v[98:101], s[76:77] offset:576 nt
	global_load_dwordx4 v[228:231], v157, s[74:75] offset:64 nt
	s_add_u32 s76, s76, 0x20000
	s_addc_u32 s77, s77, 0
	s_waitcnt vmcnt(10)
	v_pk_fma_f32 v[96:97], v[96:97], v[142:143], v[234:235]
	v_pk_fma_f32 v[94:95], v[94:95], v[140:141], v[232:233]
	global_store_dwordx4 v157, v[94:97], s[76:77] nt
	global_load_dwordx4 v[232:235], v157, s[74:75] offset:512 nt
	s_waitcnt vmcnt(10)
	v_pk_fma_f32 v[92:93], v[92:93], v[146:147], v[238:239]
	v_pk_fma_f32 v[90:91], v[90:91], v[144:145], v[236:237]
	global_store_dwordx4 v157, v[90:93], s[76:77] offset:64 nt
	global_load_dwordx4 v[236:239], v157, s[74:75] offset:576 nt
	s_waitcnt vmcnt(10)
	v_pk_fma_f32 v[88:89], v[88:89], v[150:151], v[242:243]
	v_pk_fma_f32 v[86:87], v[86:87], v[148:149], v[240:241]
	global_store_dwordx4 v157, v[86:89], s[76:77] offset:512 nt
	s_add_u32 s74, s74, 0xa0000
	s_addc_u32 s75, s75, 0
	global_load_dwordx4 v[240:243], v157, s[74:75] nt
	s_waitcnt vmcnt(10)
	v_pk_fma_f32 v[84:85], v[84:85], v[170:171], v[246:247]
	v_pk_fma_f32 v[82:83], v[82:83], v[168:169], v[244:245]
	global_store_dwordx4 v157, v[82:85], s[76:77] offset:576 nt
	global_load_dwordx4 v[244:247], v157, s[74:75] offset:64 nt
	s_add_u32 s76, s76, 0x20000
	s_addc_u32 s77, s77, 0
	s_waitcnt vmcnt(10)
	v_pk_fma_f32 v[80:81], v[80:81], v[142:143], v[226:227]
	v_pk_fma_f32 v[78:79], v[78:79], v[140:141], v[224:225]
	global_store_dwordx4 v157, v[78:81], s[76:77] nt
	global_load_dwordx4 v[224:227], v157, s[74:75] offset:512 nt
	s_waitcnt vmcnt(10)
	v_pk_fma_f32 v[76:77], v[76:77], v[146:147], v[230:231]
	v_pk_fma_f32 v[74:75], v[74:75], v[144:145], v[228:229]
	global_store_dwordx4 v157, v[74:77], s[76:77] offset:64 nt
	global_load_dwordx4 v[228:231], v157, s[74:75] offset:576 nt
	s_waitcnt vmcnt(10)
	v_pk_fma_f32 v[72:73], v[72:73], v[150:151], v[234:235]
	v_pk_fma_f32 v[70:71], v[70:71], v[148:149], v[232:233]
	global_store_dwordx4 v157, v[70:73], s[76:77] offset:512 nt
	s_add_u32 s74, s74, 0x20000
	s_addc_u32 s75, s75, 0
	global_load_dwordx4 v[232:235], v157, s[74:75] nt
	s_waitcnt vmcnt(10)
	v_pk_fma_f32 v[68:69], v[68:69], v[170:171], v[238:239]
	v_pk_fma_f32 v[66:67], v[66:67], v[168:169], v[236:237]
	global_store_dwordx4 v157, v[66:69], s[76:77] offset:576 nt
	global_load_dwordx4 v[236:239], v157, s[74:75] offset:64 nt
	s_add_u32 s76, s76, 0xa0000
	s_addc_u32 s77, s77, 0
	s_waitcnt vmcnt(10)
	v_pk_fma_f32 v[64:65], v[64:65], v[142:143], v[242:243]
	v_pk_fma_f32 v[62:63], v[62:63], v[140:141], v[240:241]
	global_store_dwordx4 v157, v[62:65], s[76:77] nt
	global_load_dwordx4 v[240:243], v157, s[74:75] offset:512 nt
	s_waitcnt vmcnt(10)
	v_pk_fma_f32 v[60:61], v[60:61], v[146:147], v[246:247]
	v_pk_fma_f32 v[58:59], v[58:59], v[144:145], v[244:245]
	global_store_dwordx4 v157, v[58:61], s[76:77] offset:64 nt
	global_load_dwordx4 v[244:247], v157, s[74:75] offset:576 nt
	s_waitcnt vmcnt(10)
	v_pk_fma_f32 v[56:57], v[56:57], v[150:151], v[226:227]
	v_pk_fma_f32 v[54:55], v[54:55], v[148:149], v[224:225]
	global_store_dwordx4 v157, v[54:57], s[76:77] offset:512 nt
	s_add_u32 s74, s74, 0x20000
	s_addc_u32 s75, s75, 0
	global_load_dwordx4 v[224:227], v157, s[74:75] nt
	s_waitcnt vmcnt(10)
	v_pk_fma_f32 v[52:53], v[52:53], v[170:171], v[230:231]
	v_pk_fma_f32 v[50:51], v[50:51], v[168:169], v[228:229]
	global_store_dwordx4 v157, v[50:53], s[76:77] offset:576 nt
	global_load_dwordx4 v[228:231], v157, s[74:75] offset:64 nt
	s_add_u32 s76, s76, 0x20000
	s_addc_u32 s77, s77, 0
	s_waitcnt vmcnt(10)
	v_pk_fma_f32 v[48:49], v[48:49], v[142:143], v[234:235]
	v_pk_fma_f32 v[46:47], v[46:47], v[140:141], v[232:233]
	global_store_dwordx4 v157, v[46:49], s[76:77] nt
	global_load_dwordx4 v[232:235], v157, s[74:75] offset:512 nt
	s_waitcnt vmcnt(10)
	v_pk_fma_f32 v[44:45], v[44:45], v[146:147], v[238:239]
	v_pk_fma_f32 v[42:43], v[42:43], v[144:145], v[236:237]
	global_store_dwordx4 v157, v[42:45], s[76:77] offset:64 nt
	global_load_dwordx4 v[236:239], v157, s[74:75] offset:576 nt
	s_waitcnt vmcnt(10)
	v_pk_fma_f32 v[40:41], v[40:41], v[150:151], v[242:243]
	v_pk_fma_f32 v[38:39], v[38:39], v[148:149], v[240:241]
	global_store_dwordx4 v157, v[38:41], s[76:77] offset:512 nt
	s_add_u32 s74, s74, 0x20000
	s_addc_u32 s75, s75, 0
	global_load_dwordx4 v[240:243], v157, s[74:75] nt
	s_waitcnt vmcnt(10)
	v_pk_fma_f32 v[36:37], v[36:37], v[170:171], v[246:247]
	v_pk_fma_f32 v[34:35], v[34:35], v[168:169], v[244:245]
	global_store_dwordx4 v157, v[34:37], s[76:77] offset:576 nt
	global_load_dwordx4 v[244:247], v157, s[74:75] offset:64 nt
	s_add_u32 s76, s76, 0x20000
	s_addc_u32 s77, s77, 0
	s_waitcnt vmcnt(10)
	v_pk_fma_f32 v[32:33], v[32:33], v[142:143], v[226:227]
	v_pk_fma_f32 v[30:31], v[30:31], v[140:141], v[224:225]
	global_store_dwordx4 v157, v[30:33], s[76:77] nt
	global_load_dwordx4 v[224:227], v157, s[74:75] offset:512 nt
	s_waitcnt vmcnt(10)
	v_pk_fma_f32 v[28:29], v[28:29], v[146:147], v[230:231]
	v_pk_fma_f32 v[26:27], v[26:27], v[144:145], v[228:229]
	global_store_dwordx4 v157, v[26:29], s[76:77] offset:64 nt
	global_load_dwordx4 v[228:231], v157, s[74:75] offset:576 nt
	s_waitcnt vmcnt(10)
	v_pk_fma_f32 v[24:25], v[24:25], v[150:151], v[234:235]
	v_pk_fma_f32 v[22:23], v[22:23], v[148:149], v[232:233]
	global_store_dwordx4 v157, v[22:25], s[76:77] offset:512 nt
	s_waitcnt vmcnt(9)
	v_pk_fma_f32 v[20:21], v[20:21], v[170:171], v[238:239]
	v_pk_fma_f32 v[18:19], v[18:19], v[168:169], v[236:237]
	global_store_dwordx4 v157, v[18:21], s[76:77] offset:576 nt
	s_add_u32 s76, s76, 0x20000
	s_addc_u32 s77, s77, 0
	s_waitcnt vmcnt(8)
	v_pk_fma_f32 v[16:17], v[16:17], v[142:143], v[242:243]
	v_pk_fma_f32 v[14:15], v[14:15], v[140:141], v[240:241]
	global_store_dwordx4 v157, v[14:17], s[76:77] nt
	s_waitcnt vmcnt(7)
	v_pk_fma_f32 v[12:13], v[12:13], v[146:147], v[246:247]
	v_pk_fma_f32 v[10:11], v[10:11], v[144:145], v[244:245]
	global_store_dwordx4 v157, v[10:13], s[76:77] offset:64 nt
	s_waitcnt vmcnt(6)
	v_pk_fma_f32 v[8:9], v[8:9], v[150:151], v[226:227]
	v_pk_fma_f32 v[6:7], v[6:7], v[148:149], v[224:225]
	global_store_dwordx4 v157, v[6:9], s[76:77] offset:512 nt
	s_waitcnt vmcnt(5)
	v_pk_fma_f32 v[4:5], v[4:5], v[170:171], v[230:231]
	v_pk_fma_f32 v[2:3], v[2:3], v[168:169], v[228:229]
	global_store_dwordx4 v157, v[2:5], s[76:77] offset:576 nt
	s_branch .LBB0_24

.LBB0_220:
	s_andn2_b64 vcc, exec, s[0:1]
	s_cbranch_vccnz .LBB0_429
	s_cmp_lt_i32 s17, 7
	s_mov_b64 s[0:1], -1
	s_cbranch_scc1 .LBB0_263
	s_cmp_gt_i32 s17, 7
	s_cbranch_scc0 .LBB0_240
	v_readlane_b32 s0, v250, 16
	v_readlane_b32 s1, v250, 17
	s_andn2_b64 vcc, exec, s[0:1]
	v_readfirstlane_b32 s36, v166
	s_cbranch_vccnz .LBB0_239
	v_lshlrev_b32_e32 v0, 4, v166
	s_waitcnt vmcnt(0)
	v_add_u32_e32 v3, 0x2000, v0
	v_ashrrev_i32_e32 v2, 31, v3
	v_lshrrev_b32_e32 v2, 22, v2
	v_add_u32_e32 v2, v3, v2
	v_ashrrev_i32_e32 v2, 10, v2
	v_mul_i32_i24_e32 v4, 0x400, v2
	v_sub_u32_e32 v3, v3, v4
	v_lshrrev_b32_e32 v4, 4, v3
	v_bitop3_b32 v4, v4, v3, 32 bitop3:0x6c
	v_ashrrev_i32_e32 v3, 31, v4
	v_lshrrev_b32_e32 v3, 26, v3
	v_add_u32_e32 v5, v4, v3
	v_lshlrev_b32_e32 v6, 3, v2
	v_ashrrev_i32_e32 v3, 6, v5
	v_and_b32_e32 v6, -16, v6
	v_add_u32_e32 v6, v3, v6
	v_and_b32_e32 v7, 3, v3
	s_mov_b32 s1, 0xfffe0
	v_lshrrev_b32_e32 v8, 2, v6
	v_lshlrev_b32_e32 v9, 1, v6
	v_and_b32_e32 v5, 0xc0, v5
	v_and_or_b32 v7, v6, s1, v7
	v_and_b32_e32 v8, 4, v8
	v_and_b32_e32 v9, 24, v9
	v_sub_u32_e32 v4, v4, v5
	v_or3_b32 v7, v7, v8, v9
	v_lshlrev_b32_e32 v8, 5, v2
	v_ashrrev_i16_sdwa v4, v203, sext(v4) dst_sel:DWORD dst_unused:UNUSED_PAD src0_sel:DWORD src1_sel:BYTE_0
	v_and_b32_e32 v8, 32, v8
	v_bfe_i32 v4, v4, 0, 16
	v_add_lshl_u32 v5, v8, v4, 1
	v_lshl_add_u32 v130, v7, 12, v5
	v_lshl_add_u32 v132, v6, 12, v5
	v_bfe_i32 v5, v166, 27, 1
	v_lshrrev_b32_e32 v5, 22, v5
	v_add_u32_e32 v5, v0, v5
	v_and_b32_e32 v5, 0xfffffc00, v5
	v_sub_u32_e32 v0, v0, v5
	v_lshrrev_b32_e32 v5, 4, v0
	v_ashrrev_i32_e32 v6, 31, v166
	v_bitop3_b32 v0, v5, v0, 32 bitop3:0x6c
	v_lshrrev_b32_e32 v6, 26, v6
	v_ashrrev_i32_e32 v5, 31, v0
	v_add_u32_e32 v6, v166, v6
	v_lshrrev_b32_e32 v5, 26, v5
	v_ashrrev_i32_e32 v6, 6, v6
	v_add_u32_e32 v7, v0, v5
	v_lshlrev_b32_e32 v8, 3, v6
	v_ashrrev_i32_e32 v5, 6, v7
	v_and_b32_e32 v8, -16, v8
	v_add_u32_e32 v8, v5, v8
	v_and_b32_e32 v9, 3, v5
	v_lshrrev_b32_e32 v10, 2, v8
	v_lshlrev_b32_e32 v11, 1, v8
	v_and_b32_e32 v7, 0xc0, v7
	v_and_or_b32 v9, v8, s1, v9
	v_and_b32_e32 v10, 4, v10
	v_and_b32_e32 v11, 24, v11
	v_sub_u32_e32 v0, v0, v7
	s_ashr_i32 s0, s36, 6
	v_or3_b32 v9, v9, v10, v11
	v_lshlrev_b32_e32 v10, 5, v6
	v_ashrrev_i16_sdwa v0, v203, sext(v0) dst_sel:DWORD dst_unused:UNUSED_PAD src0_sel:DWORD src1_sel:BYTE_0
	s_lshl_b32 s52, s0, 10
	v_and_b32_e32 v10, 32, v10
	v_bfe_i32 v7, v0, 0, 16
	v_add_lshl_u32 v10, v10, v7, 1
	s_add_i32 s53, s52, 0
	v_readlane_b32 s12, v253, 24
	v_lshl_add_u32 v0, v9, 12, v10
	s_add_i32 m0, s53, 0x10000
	v_readlane_b32 s13, v253, 25
	v_lshl_add_u32 v134, v8, 12, v10
	s_add_i32 s54, s53, 0x2000
	s_add_i32 s55, s53, 0x4000
	s_add_i32 s56, s53, 0x6000
	s_ashr_i32 s1, s36, 8
	global_load_lds_dwordx4 v0, s[12:13]
	s_add_i32 m0, s53, 0x12000
	s_nop 0
	global_load_lds_dwordx4 v130, s[12:13]
	v_readlane_b32 s12, v253, 20
	s_mov_b32 m0, s53
	v_readlane_b32 s13, v253, 21
	s_nop 4
	global_load_lds_dwordx4 v134, s[12:13]
	s_mov_b32 m0, s54
	s_nop 0
	global_load_lds_dwordx4 v132, s[12:13]
	v_readlane_b32 s12, v253, 18
	s_add_i32 m0, s53, 0x14000
	v_readlane_b32 s13, v253, 19
	s_nop 4
	global_load_lds_dwordx4 v0, s[12:13]
	s_add_i32 m0, s53, 0x16000
	s_cmp_lg_u32 s1, 1
	global_load_lds_dwordx4 v130, s[12:13]
	v_readlane_b32 s12, v253, 22
	s_mov_b32 m0, s55
	v_readlane_b32 s13, v253, 23
	s_nop 4
	global_load_lds_dwordx4 v134, s[12:13]
	s_mov_b32 m0, s56
	s_nop 0
	global_load_lds_dwordx4 v132, s[12:13]
	s_cbranch_scc1 .LBB0_226
	s_barrier
	s_setprio 1

.LBB0_234:
	s_add_u32 s39, s46, 0xfff80080
	s_addc_u32 s48, s47, -1
	s_add_i32 s62, 0, 0x10000
	v_add_u32_e32 v156, s62, v141
	ds_read_b128 v[144:147], v156
	ds_read_b128 v[148:151], v156 offset:1024
	ds_read_b128 v[152:155], v156 offset:2048
	ds_read_b128 v[168:171], v156 offset:3072
	s_cmp_eq_u32 s13, 28
	s_cselect_b32 s51, s43, s48
	s_cselect_b32 s50, s42, s39
	s_cselect_b32 s49, s45, s12
	s_cselect_b32 s48, s44, s1
	v_lshl_add_u64 v[156:157], s[46:47], 0, v[136:137]
	s_add_i32 m0, s53, 0xc000
	ds_read_b128 v[172:175], v143
	ds_read_b128 v[176:179], v143 offset:1024
	ds_read_b128 v[180:183], v143 offset:2048
	ds_read_b128 v[184:187], v143 offset:3072
	ds_read_b128 v[188:191], v143 offset:4096
	ds_read_b128 v[192:195], v143 offset:5120
	ds_read_b128 v[196:199], v143 offset:6144
	ds_read_b128 v[224:227], v143 offset:7168
	global_load_lds_dwordx4 v[156:157], off
	v_lshl_add_u64 v[156:157], s[46:47], 0, v[138:139]
	s_add_i32 m0, s53, 0xe000
	s_nop 0
	global_load_lds_dwordx4 v[156:157], off
	s_waitcnt lgkmcnt(8)
	s_barrier
	s_waitcnt lgkmcnt(0)
	s_waitcnt lgkmcnt(0)
	v_mfma_f32_16x16x32_bf16 v[126:129], v[144:147], v[172:175], v[126:129]
	v_mfma_f32_16x16x32_bf16 v[122:125], v[152:155], v[172:175], v[122:125]
	v_mfma_f32_16x16x32_bf16 v[118:121], v[144:147], v[180:183], v[118:121]
	v_mfma_f32_16x16x32_bf16 v[114:117], v[152:155], v[180:183], v[114:117]
	v_mfma_f32_16x16x32_bf16 v[102:105], v[144:147], v[188:191], v[102:105]
	v_mfma_f32_16x16x32_bf16 v[98:101], v[152:155], v[188:191], v[98:101]
	v_mfma_f32_16x16x32_bf16 v[86:89], v[144:147], v[196:199], v[86:89]
	v_mfma_f32_16x16x32_bf16 v[82:85], v[152:155], v[196:199], v[82:85]
	v_mfma_f32_16x16x32_bf16 v[126:129], v[148:151], v[176:179], v[126:129]
	v_mfma_f32_16x16x32_bf16 v[122:125], v[168:171], v[176:179], v[122:125]
	v_mfma_f32_16x16x32_bf16 v[118:121], v[148:151], v[184:187], v[118:121]
	v_mfma_f32_16x16x32_bf16 v[114:117], v[168:171], v[184:187], v[114:117]
	v_mfma_f32_16x16x32_bf16 v[102:105], v[148:151], v[192:195], v[102:105]
	v_mfma_f32_16x16x32_bf16 v[98:101], v[168:171], v[192:195], v[98:101]
	v_mfma_f32_16x16x32_bf16 v[86:89], v[148:151], v[224:227], v[86:89]
	v_mfma_f32_16x16x32_bf16 v[82:85], v[168:171], v[224:227], v[82:85]
	s_barrier
	s_add_i32 s39, 0, 0x14000
	v_add_u32_e32 v156, s39, v141
	s_add_i32 s62, s62, s52
	ds_read_b128 v[228:231], v156
	ds_read_b128 v[232:235], v156 offset:1024
	ds_read_b128 v[236:239], v156 offset:2048
	ds_read_b128 v[240:243], v156 offset:3072
	v_lshl_add_u64 v[156:157], s[48:49], 0, v[0:1]
	s_mov_b32 m0, s62
	v_lshl_add_u64 v[200:201], s[48:49], 0, v[130:131]
	global_load_lds_dwordx4 v[156:157], off
	s_add_i32 m0, s62, 0x2000
	s_nop 0
	global_load_lds_dwordx4 v[200:201], off
	s_barrier
	s_waitcnt lgkmcnt(0)
	s_waitcnt lgkmcnt(0)
	v_mfma_f32_16x16x32_bf16 v[110:113], v[228:231], v[172:175], v[110:113]
	v_mfma_f32_16x16x32_bf16 v[106:109], v[236:239], v[172:175], v[106:109]
	v_mfma_f32_16x16x32_bf16 v[94:97], v[228:231], v[180:183], v[94:97]
	v_mfma_f32_16x16x32_bf16 v[90:93], v[236:239], v[180:183], v[90:93]
	v_mfma_f32_16x16x32_bf16 v[78:81], v[228:231], v[188:191], v[78:81]
	v_mfma_f32_16x16x32_bf16 v[74:77], v[236:239], v[188:191], v[74:77]
	v_mfma_f32_16x16x32_bf16 v[70:73], v[228:231], v[196:199], v[70:73]
	v_mfma_f32_16x16x32_bf16 v[66:69], v[236:239], v[196:199], v[66:69]
	v_mfma_f32_16x16x32_bf16 v[110:113], v[232:235], v[176:179], v[110:113]
	v_mfma_f32_16x16x32_bf16 v[106:109], v[240:243], v[176:179], v[106:109]
	v_mfma_f32_16x16x32_bf16 v[94:97], v[232:235], v[184:187], v[94:97]
	v_mfma_f32_16x16x32_bf16 v[90:93], v[240:243], v[184:187], v[90:93]
	v_mfma_f32_16x16x32_bf16 v[78:81], v[232:235], v[192:195], v[78:81]
	v_mfma_f32_16x16x32_bf16 v[74:77], v[240:243], v[192:195], v[74:77]
	v_mfma_f32_16x16x32_bf16 v[70:73], v[232:235], v[224:227], v[70:73]
	v_mfma_f32_16x16x32_bf16 v[66:69], v[240:243], v[224:227], v[66:69]
	s_mov_b32 m0, s53
	v_lshl_add_u64 v[210:211], s[50:51], 0, v[134:135]
	s_barrier
	ds_read_b128 v[172:175], v143 offset:16384
	ds_read_b128 v[176:179], v143 offset:17408
	ds_read_b128 v[180:183], v143 offset:18432
	ds_read_b128 v[184:187], v143 offset:19456
	ds_read_b128 v[188:191], v143 offset:20480
	ds_read_b128 v[192:195], v143 offset:21504
	ds_read_b128 v[196:199], v143 offset:22528
	ds_read_b128 v[224:227], v143 offset:23552
	global_load_lds_dwordx4 v[210:211], off
	v_lshl_add_u64 v[212:213], s[50:51], 0, v[132:133]
	s_mov_b32 m0, s54
	s_nop 0
	global_load_lds_dwordx4 v[212:213], off
	s_barrier
	s_waitcnt lgkmcnt(0)
	s_waitcnt lgkmcnt(0)
	v_mfma_f32_16x16x32_bf16 v[62:65], v[144:147], v[172:175], v[62:65]
	v_mfma_f32_16x16x32_bf16 v[58:61], v[152:155], v[172:175], v[58:61]
	v_mfma_f32_16x16x32_bf16 v[54:57], v[144:147], v[180:183], v[54:57]
	v_mfma_f32_16x16x32_bf16 v[50:53], v[152:155], v[180:183], v[50:53]
	v_mfma_f32_16x16x32_bf16 v[38:41], v[144:147], v[188:191], v[38:41]
	v_mfma_f32_16x16x32_bf16 v[34:37], v[152:155], v[188:191], v[34:37]
	v_mfma_f32_16x16x32_bf16 v[22:25], v[144:147], v[196:199], v[22:25]
	v_mfma_f32_16x16x32_bf16 v[18:21], v[152:155], v[196:199], v[18:21]
	v_mfma_f32_16x16x32_bf16 v[62:65], v[148:151], v[176:179], v[62:65]
	v_mfma_f32_16x16x32_bf16 v[58:61], v[168:171], v[176:179], v[58:61]
	v_mfma_f32_16x16x32_bf16 v[54:57], v[148:151], v[184:187], v[54:57]
	v_mfma_f32_16x16x32_bf16 v[50:53], v[168:171], v[184:187], v[50:53]
	v_mfma_f32_16x16x32_bf16 v[38:41], v[148:151], v[192:195], v[38:41]
	v_mfma_f32_16x16x32_bf16 v[34:37], v[168:171], v[192:195], v[34:37]
	v_mfma_f32_16x16x32_bf16 v[22:25], v[148:151], v[224:227], v[22:25]
	v_mfma_f32_16x16x32_bf16 v[18:21], v[168:171], v[224:227], v[18:21]
	s_barrier
	s_add_u32 s62, s48, 0x80000
	s_addc_u32 s63, s49, 0
	s_add_i32 s39, s39, s52
	v_lshl_add_u64 v[144:145], s[62:63], 0, v[0:1]
	s_mov_b32 m0, s39
	s_nop 0
	global_load_lds_dwordx4 v[144:145], off
	v_lshl_add_u64 v[144:145], s[62:63], 0, v[130:131]
	s_add_i32 m0, s39, 0x2000
	s_nop 0
	global_load_lds_dwordx4 v[144:145], off
	s_waitcnt vmcnt(6)
	s_barrier
	v_mfma_f32_16x16x32_bf16 v[46:49], v[228:231], v[172:175], v[46:49]
	v_mfma_f32_16x16x32_bf16 v[42:45], v[236:239], v[172:175], v[42:45]
	v_mfma_f32_16x16x32_bf16 v[30:33], v[228:231], v[180:183], v[30:33]
	v_mfma_f32_16x16x32_bf16 v[26:29], v[236:239], v[180:183], v[26:29]
	v_mfma_f32_16x16x32_bf16 v[14:17], v[228:231], v[188:191], v[14:17]
	v_mfma_f32_16x16x32_bf16 v[10:13], v[236:239], v[188:191], v[10:13]
	v_mfma_f32_16x16x32_bf16 v[6:9], v[228:231], v[196:199], v[6:9]
	v_mfma_f32_16x16x32_bf16 v[2:5], v[236:239], v[196:199], v[2:5]
	v_mfma_f32_16x16x32_bf16 v[46:49], v[232:235], v[176:179], v[46:49]
	v_mfma_f32_16x16x32_bf16 v[42:45], v[240:243], v[176:179], v[42:45]
	v_mfma_f32_16x16x32_bf16 v[30:33], v[232:235], v[184:187], v[30:33]
	v_mfma_f32_16x16x32_bf16 v[26:29], v[240:243], v[184:187], v[26:29]
	v_mfma_f32_16x16x32_bf16 v[14:17], v[232:235], v[192:195], v[14:17]
	v_mfma_f32_16x16x32_bf16 v[10:13], v[240:243], v[192:195], v[10:13]
	v_mfma_f32_16x16x32_bf16 v[6:9], v[232:235], v[224:227], v[6:9]
	v_mfma_f32_16x16x32_bf16 v[2:5], v[240:243], v[224:227], v[2:5]
	s_add_i32 s39, 0, 0x18000
	v_add_u32_e32 v161, s39, v141
	s_barrier
	ds_read_b128 v[144:147], v161
	ds_read_b128 v[148:151], v161 offset:1024
	ds_read_b128 v[152:155], v161 offset:2048
	ds_read_b128 v[168:171], v161 offset:3072
	s_add_u32 s50, s50, 0x80000
	s_addc_u32 s51, s51, 0
	s_mov_b32 m0, s55
	v_lshl_add_u64 v[220:221], s[50:51], 0, v[134:135]
	ds_read_b128 v[172:175], v143 offset:32768
	ds_read_b128 v[176:179], v143 offset:33792
	ds_read_b128 v[180:183], v143 offset:34816
	ds_read_b128 v[184:187], v143 offset:35840
	ds_read_b128 v[188:191], v143 offset:36864
	ds_read_b128 v[192:195], v143 offset:37888
	ds_read_b128 v[196:199], v143 offset:38912
	ds_read_b128 v[224:227], v143 offset:39936
	global_load_lds_dwordx4 v[220:221], off
	v_lshl_add_u64 v[220:221], s[50:51], 0, v[132:133]
	s_mov_b32 m0, s56
	s_nop 0
	global_load_lds_dwordx4 v[220:221], off
	s_waitcnt lgkmcnt(8)
	s_barrier
	s_waitcnt lgkmcnt(0)
	s_waitcnt lgkmcnt(0)
	v_mfma_f32_16x16x32_bf16 v[126:129], v[144:147], v[172:175], v[126:129]
	v_mfma_f32_16x16x32_bf16 v[122:125], v[152:155], v[172:175], v[122:125]
	v_mfma_f32_16x16x32_bf16 v[118:121], v[144:147], v[180:183], v[118:121]
	v_mfma_f32_16x16x32_bf16 v[114:117], v[152:155], v[180:183], v[114:117]
	v_mfma_f32_16x16x32_bf16 v[102:105], v[144:147], v[188:191], v[102:105]
	v_mfma_f32_16x16x32_bf16 v[98:101], v[152:155], v[188:191], v[98:101]
	v_mfma_f32_16x16x32_bf16 v[86:89], v[144:147], v[196:199], v[86:89]
	v_mfma_f32_16x16x32_bf16 v[82:85], v[152:155], v[196:199], v[82:85]
	v_mfma_f32_16x16x32_bf16 v[126:129], v[148:151], v[176:179], v[126:129]
	v_mfma_f32_16x16x32_bf16 v[122:125], v[168:171], v[176:179], v[122:125]
	v_mfma_f32_16x16x32_bf16 v[118:121], v[148:151], v[184:187], v[118:121]
	v_mfma_f32_16x16x32_bf16 v[114:117], v[168:171], v[184:187], v[114:117]
	v_mfma_f32_16x16x32_bf16 v[102:105], v[148:151], v[192:195], v[102:105]
	v_mfma_f32_16x16x32_bf16 v[98:101], v[168:171], v[192:195], v[98:101]
	v_mfma_f32_16x16x32_bf16 v[86:89], v[148:151], v[224:227], v[86:89]
	v_mfma_f32_16x16x32_bf16 v[82:85], v[168:171], v[224:227], v[82:85]
	s_barrier
	s_add_i32 s50, 0, 0x1c000
	s_add_i32 s39, s39, s52
	v_add_u32_e32 v161, s50, v141
	v_lshl_add_u64 v[156:157], v[156:157], 0, s[94:95]
	s_mov_b32 m0, s39
	ds_read_b128 v[228:231], v161
	ds_read_b128 v[232:235], v161 offset:1024
	ds_read_b128 v[236:239], v161 offset:2048
	ds_read_b128 v[240:243], v161 offset:3072
	global_load_lds_dwordx4 v[156:157], off
	v_lshl_add_u64 v[156:157], v[200:201], 0, s[94:95]
	s_add_i32 m0, s39, 0x2000
	s_nop 0
	global_load_lds_dwordx4 v[156:157], off
	s_barrier
	s_waitcnt lgkmcnt(0)
	s_waitcnt lgkmcnt(0)
	v_mfma_f32_16x16x32_bf16 v[110:113], v[228:231], v[172:175], v[110:113]
	v_mfma_f32_16x16x32_bf16 v[106:109], v[236:239], v[172:175], v[106:109]
	v_mfma_f32_16x16x32_bf16 v[94:97], v[228:231], v[180:183], v[94:97]
	v_mfma_f32_16x16x32_bf16 v[90:93], v[236:239], v[180:183], v[90:93]
	v_mfma_f32_16x16x32_bf16 v[78:81], v[228:231], v[188:191], v[78:81]
	v_mfma_f32_16x16x32_bf16 v[74:77], v[236:239], v[188:191], v[74:77]
	v_mfma_f32_16x16x32_bf16 v[70:73], v[228:231], v[196:199], v[70:73]
	v_mfma_f32_16x16x32_bf16 v[66:69], v[236:239], v[196:199], v[66:69]
	v_mfma_f32_16x16x32_bf16 v[110:113], v[232:235], v[176:179], v[110:113]
	v_mfma_f32_16x16x32_bf16 v[106:109], v[240:243], v[176:179], v[106:109]
	v_mfma_f32_16x16x32_bf16 v[94:97], v[232:235], v[184:187], v[94:97]
	v_mfma_f32_16x16x32_bf16 v[90:93], v[240:243], v[184:187], v[90:93]
	v_mfma_f32_16x16x32_bf16 v[78:81], v[232:235], v[192:195], v[78:81]
	v_mfma_f32_16x16x32_bf16 v[74:77], v[240:243], v[192:195], v[74:77]
	v_mfma_f32_16x16x32_bf16 v[70:73], v[232:235], v[224:227], v[70:73]
	v_mfma_f32_16x16x32_bf16 v[66:69], v[240:243], v[224:227], v[66:69]
	s_mov_b32 m0, s57
	v_lshl_add_u64 v[156:157], v[210:211], 0, s[94:95]
	s_barrier
	ds_read_b128 v[172:175], v143 offset:49152
	ds_read_b128 v[176:179], v143 offset:50176
	ds_read_b128 v[180:183], v143 offset:51200
	ds_read_b128 v[184:187], v143 offset:52224
	ds_read_b128 v[188:191], v143 offset:53248
	ds_read_b128 v[192:195], v143 offset:54272
	ds_read_b128 v[196:199], v143 offset:55296
	ds_read_b128 v[224:227], v143 offset:56320
	global_load_lds_dwordx4 v[156:157], off
	v_lshl_add_u64 v[156:157], v[212:213], 0, s[94:95]
	s_mov_b32 m0, s58
	s_nop 0
	global_load_lds_dwordx4 v[156:157], off
	s_barrier
	s_waitcnt lgkmcnt(0)
	s_waitcnt lgkmcnt(0)
	v_mfma_f32_16x16x32_bf16 v[62:65], v[144:147], v[172:175], v[62:65]
	v_mfma_f32_16x16x32_bf16 v[58:61], v[152:155], v[172:175], v[58:61]
	v_mfma_f32_16x16x32_bf16 v[54:57], v[144:147], v[180:183], v[54:57]
	v_mfma_f32_16x16x32_bf16 v[50:53], v[152:155], v[180:183], v[50:53]
	v_mfma_f32_16x16x32_bf16 v[38:41], v[144:147], v[188:191], v[38:41]
	v_mfma_f32_16x16x32_bf16 v[34:37], v[152:155], v[188:191], v[34:37]
	v_mfma_f32_16x16x32_bf16 v[22:25], v[144:147], v[196:199], v[22:25]
	v_mfma_f32_16x16x32_bf16 v[18:21], v[152:155], v[196:199], v[18:21]
	v_mfma_f32_16x16x32_bf16 v[62:65], v[148:151], v[176:179], v[62:65]
	v_mfma_f32_16x16x32_bf16 v[58:61], v[168:171], v[176:179], v[58:61]
	v_mfma_f32_16x16x32_bf16 v[54:57], v[148:151], v[184:187], v[54:57]
	v_mfma_f32_16x16x32_bf16 v[50:53], v[168:171], v[184:187], v[50:53]
	v_mfma_f32_16x16x32_bf16 v[38:41], v[148:151], v[192:195], v[38:41]
	v_mfma_f32_16x16x32_bf16 v[34:37], v[168:171], v[192:195], v[34:37]
	v_mfma_f32_16x16x32_bf16 v[22:25], v[148:151], v[224:227], v[22:25]
	v_mfma_f32_16x16x32_bf16 v[18:21], v[168:171], v[224:227], v[18:21]
	s_barrier
	s_add_u32 s48, s48, 0x80080
	s_addc_u32 s49, s49, 0
	s_add_i32 s39, s50, s52
	v_lshl_add_u64 v[144:145], s[48:49], 0, v[0:1]
	s_mov_b32 m0, s39
	s_nop 0
	global_load_lds_dwordx4 v[144:145], off
	v_lshl_add_u64 v[144:145], s[48:49], 0, v[130:131]
	s_add_i32 m0, s39, 0x2000
	s_nop 0
	global_load_lds_dwordx4 v[144:145], off
	s_waitcnt vmcnt(6)
	s_barrier
	v_mfma_f32_16x16x32_bf16 v[46:49], v[228:231], v[172:175], v[46:49]
	v_mfma_f32_16x16x32_bf16 v[42:45], v[236:239], v[172:175], v[42:45]
	v_mfma_f32_16x16x32_bf16 v[30:33], v[228:231], v[180:183], v[30:33]
	v_mfma_f32_16x16x32_bf16 v[26:29], v[236:239], v[180:183], v[26:29]
	v_mfma_f32_16x16x32_bf16 v[14:17], v[228:231], v[188:191], v[14:17]
	v_mfma_f32_16x16x32_bf16 v[10:13], v[236:239], v[188:191], v[10:13]
	v_mfma_f32_16x16x32_bf16 v[6:9], v[228:231], v[196:199], v[6:9]
	v_mfma_f32_16x16x32_bf16 v[2:5], v[236:239], v[196:199], v[2:5]
	v_mfma_f32_16x16x32_bf16 v[46:49], v[232:235], v[176:179], v[46:49]
	v_mfma_f32_16x16x32_bf16 v[42:45], v[240:243], v[176:179], v[42:45]
	v_mfma_f32_16x16x32_bf16 v[30:33], v[232:235], v[184:187], v[30:33]
	v_mfma_f32_16x16x32_bf16 v[26:29], v[240:243], v[184:187], v[26:29]
	v_mfma_f32_16x16x32_bf16 v[14:17], v[232:235], v[192:195], v[14:17]
	v_mfma_f32_16x16x32_bf16 v[10:13], v[240:243], v[192:195], v[10:13]
	v_mfma_f32_16x16x32_bf16 v[6:9], v[232:235], v[224:227], v[6:9]
	v_mfma_f32_16x16x32_bf16 v[2:5], v[240:243], v[224:227], v[2:5]
	s_add_i32 s13, s13, 2
	s_add_u32 s46, s46, 0x100
	s_addc_u32 s47, s47, 0
	s_add_u32 s1, s1, 0x100
	s_addc_u32 s12, s12, 0
	s_cmp_gt_u32 s13, 29
	s_barrier
	s_cbranch_scc0 .LBB0_234
	v_readlane_b32 s6, v255, 23
	v_lshl_add_u32 v150, s61, 8, v140
	v_lshl_or_b32 v144, s60, 8, v142
	v_readlane_b32 s7, v255, 24
	v_ashrrev_i32_e32 v145, 31, v144
	s_movk_i32 s1, 0x5800
	v_mov_b64_e32 v[146:147], s[6:7]
	v_cvt_pk_bf16_f32 v70, v70, v71
	v_cvt_pk_bf16_f32 v71, v72, v73
	v_cvt_pk_bf16_f32 v72, v66, v67
	v_add_u32_e32 v66, 0x80, v150
	v_mad_i64_i32 v[148:149], s[12:13], v150, s1, v[146:147]
	v_lshlrev_b64 v[144:145], 1, v[144:145]
	v_cvt_pk_bf16_f32 v110, v110, v111
	v_cvt_pk_bf16_f32 v111, v112, v113
	v_cvt_pk_bf16_f32 v112, v106, v107
	v_or_b32_e32 v106, 16, v150
	v_mad_i64_i32 v[66:67], s[12:13], v66, s1, v[146:147]
	v_cvt_pk_bf16_f32 v46, v46, v47
	v_cvt_pk_bf16_f32 v47, v48, v49
	v_cvt_pk_bf16_f32 v48, v42, v43
	v_add_u32_e32 v42, 0x90, v150
	v_lshl_add_u64 v[148:149], v[148:149], 0, v[144:145]
	v_cvt_pk_bf16_f32 v113, v108, v109
	v_mad_i64_i32 v[106:107], s[12:13], v106, s1, v[146:147]
	v_cvt_pk_bf16_f32 v94, v94, v95
	v_cvt_pk_bf16_f32 v95, v96, v97
	v_cvt_pk_bf16_f32 v96, v90, v91
	v_or_b32_e32 v90, 32, v150
	v_lshl_add_u64 v[66:67], v[66:67], 0, v[144:145]
	v_cvt_pk_bf16_f32 v49, v44, v45
	v_mad_i64_i32 v[42:43], s[12:13], v42, s1, v[146:147]
	v_cvt_pk_bf16_f32 v30, v30, v31
	v_cvt_pk_bf16_f32 v31, v32, v33
	v_cvt_pk_bf16_f32 v32, v26, v27
	v_add_u32_e32 v26, 0xa0, v150
	global_store_dwordx4 v[148:149], v[110:113], off offset:256
	v_cvt_pk_bf16_f32 v97, v92, v93
	v_mad_i64_i32 v[90:91], s[12:13], v90, s1, v[146:147]
	v_lshl_add_u64 v[110:111], v[106:107], 0, v[144:145]
	v_cvt_pk_bf16_f32 v78, v78, v79
	v_cvt_pk_bf16_f32 v79, v80, v81
	v_cvt_pk_bf16_f32 v80, v74, v75
	v_or_b32_e32 v74, 48, v150
	global_store_dwordx4 v[66:67], v[46:49], off offset:256
	v_cvt_pk_bf16_f32 v33, v28, v29
	v_mad_i64_i32 v[26:27], s[12:13], v26, s1, v[146:147]
	v_lshl_add_u64 v[46:47], v[42:43], 0, v[144:145]
	v_cvt_pk_bf16_f32 v14, v14, v15
	v_cvt_pk_bf16_f32 v15, v16, v17
	v_cvt_pk_bf16_f32 v16, v10, v11
	v_add_u32_e32 v10, 0xb0, v150
	global_store_dwordx4 v[110:111], v[94:97], off offset:256
	v_cvt_pk_bf16_f32 v81, v76, v77
	v_mad_i64_i32 v[74:75], s[12:13], v74, s1, v[146:147]
	v_lshl_add_u64 v[94:95], v[90:91], 0, v[144:145]
	global_store_dwordx4 v[46:47], v[30:33], off offset:256
	v_cvt_pk_bf16_f32 v17, v12, v13
	v_mad_i64_i32 v[10:11], s[12:13], v10, s1, v[146:147]
	v_lshl_add_u64 v[30:31], v[26:27], 0, v[144:145]
	v_cvt_pk_bf16_f32 v126, v126, v127
	v_cvt_pk_bf16_f32 v127, v128, v129
	v_cvt_pk_bf16_f32 v128, v122, v123
	v_cvt_pk_bf16_f32 v129, v124, v125
	v_cvt_pk_bf16_f32 v106, v118, v119
	v_cvt_pk_bf16_f32 v107, v120, v121
	v_cvt_pk_bf16_f32 v108, v114, v115
	v_cvt_pk_bf16_f32 v109, v116, v117
	v_cvt_pk_bf16_f32 v90, v102, v103
	v_cvt_pk_bf16_f32 v91, v104, v105
	v_cvt_pk_bf16_f32 v92, v98, v99
	v_cvt_pk_bf16_f32 v93, v100, v101
	global_store_dwordx4 v[94:95], v[78:81], off offset:256
	v_cvt_pk_bf16_f32 v76, v82, v83
	v_cvt_pk_bf16_f32 v77, v84, v85
	v_lshl_add_u64 v[78:79], v[74:75], 0, v[144:145]
	v_cvt_pk_bf16_f32 v74, v86, v87
	v_cvt_pk_bf16_f32 v75, v88, v89
	v_cvt_pk_bf16_f32 v73, v68, v69
	v_cvt_pk_bf16_f32 v62, v62, v63
	v_cvt_pk_bf16_f32 v63, v64, v65
	v_cvt_pk_bf16_f32 v64, v58, v59
	v_cvt_pk_bf16_f32 v65, v60, v61
	v_cvt_pk_bf16_f32 v42, v54, v55
	v_cvt_pk_bf16_f32 v43, v56, v57
	v_cvt_pk_bf16_f32 v44, v50, v51
	v_cvt_pk_bf16_f32 v45, v52, v53
	v_cvt_pk_bf16_f32 v26, v38, v39
	v_cvt_pk_bf16_f32 v27, v40, v41
	v_cvt_pk_bf16_f32 v28, v34, v35
	v_cvt_pk_bf16_f32 v29, v36, v37
	global_store_dwordx4 v[30:31], v[14:17], off offset:256
	v_cvt_pk_bf16_f32 v12, v18, v19
	v_cvt_pk_bf16_f32 v13, v20, v21
	v_lshl_add_u64 v[14:15], v[10:11], 0, v[144:145]
	v_cvt_pk_bf16_f32 v10, v22, v23
	v_cvt_pk_bf16_f32 v11, v24, v25
	v_cvt_pk_bf16_f32 v6, v6, v7
	v_cvt_pk_bf16_f32 v7, v8, v9
	v_cvt_pk_bf16_f32 v8, v2, v3
	v_cvt_pk_bf16_f32 v9, v4, v5
	s_and_b64 vcc, exec, s[40:41]
	s_mov_b32 s60, s0
	s_mov_b32 s61, s38
	s_mov_b64 s[48:49], s[44:45]
	s_mov_b64 s[46:47], s[42:43]
	global_store_dwordx4 v[148:149], v[126:129], off
	global_store_dwordx4 v[110:111], v[106:109], off
	global_store_dwordx4 v[94:95], v[90:93], off
	global_store_dwordx4 v[78:79], v[74:77], off
	global_store_dwordx4 v[78:79], v[70:73], off offset:256
	global_store_dwordx4 v[66:67], v[62:65], off
	global_store_dwordx4 v[46:47], v[42:45], off
	global_store_dwordx4 v[30:31], v[26:29], off
	global_store_dwordx4 v[14:15], v[10:13], off
	global_store_dwordx4 v[14:15], v[6:9], off offset:256
	s_cbranch_vccz .LBB0_227
	s_waitcnt vmcnt(0)
	v_readlane_b32 s60, v255, 21
	s_cmpk_gt_u32 s36, 0xff
	s_mov_b32 s18, s60
	v_readlane_b32 s61, v255, 22
	s_cbranch_scc1 .LBB0_238
	s_barrier

.LBB0_263:
	s_andn2_b64 vcc, exec, s[0:1]
	s_cbranch_vccnz .LBB0_429
	v_readlane_b32 s0, v250, 20
	v_readlane_b32 s1, v250, 21
	s_andn2_b64 vcc, exec, s[0:1]
	v_readfirstlane_b32 s36, v166
	s_cbranch_vccnz .LBB0_429
	v_lshlrev_b32_e32 v0, 4, v166
	s_waitcnt vmcnt(0)
	v_add_u32_e32 v3, 0x2000, v0
	v_ashrrev_i32_e32 v2, 31, v3
	v_lshrrev_b32_e32 v2, 22, v2
	v_add_u32_e32 v2, v3, v2
	v_ashrrev_i32_e32 v2, 10, v2
	v_lshlrev_b32_e32 v4, 5, v2
	v_and_b32_e32 v5, 32, v4
	v_mul_i32_i24_e32 v4, 0x400, v2
	v_sub_u32_e32 v3, v3, v4
	v_lshrrev_b32_e32 v4, 4, v3
	v_bitop3_b32 v4, v4, v3, 32 bitop3:0x6c
	v_ashrrev_i32_e32 v3, 31, v4
	v_lshrrev_b32_e32 v3, 26, v3
	v_add_u32_e32 v6, v4, v3
	v_ashrrev_i32_e32 v3, 6, v6
	v_and_b32_e32 v6, 0xc0, v6
	v_sub_u32_e32 v4, v4, v6
	v_ashrrev_i16_sdwa v4, v203, sext(v4) dst_sel:DWORD dst_unused:UNUSED_PAD src0_sel:DWORD src1_sel:BYTE_0
	v_lshlrev_b32_e32 v6, 3, v2
	v_bfe_i32 v4, v4, 0, 16
	v_and_b32_e32 v6, 0xffff0, v6
	v_add_u32_e32 v5, v5, v4
	v_add_lshl_u32 v6, v3, v6, 12
	v_lshl_add_u32 v130, v5, 1, v6
	v_ashrrev_i32_e32 v5, 31, v166
	v_lshrrev_b32_e32 v5, 26, v5
	v_add_u32_e32 v5, v166, v5
	v_ashrrev_i32_e32 v5, 6, v5
	v_lshlrev_b32_e32 v6, 5, v5
	v_and_b32_e32 v8, 32, v6
	v_bfe_i32 v6, v166, 27, 1
	v_lshrrev_b32_e32 v6, 22, v6
	v_add_u32_e32 v6, v0, v6
	v_and_b32_e32 v6, 0xfffffc00, v6
	v_sub_u32_e32 v0, v0, v6
	v_lshrrev_b32_e32 v6, 4, v0
	v_bitop3_b32 v0, v6, v0, 32 bitop3:0x6c
	v_ashrrev_i32_e32 v6, 31, v0
	v_lshrrev_b32_e32 v6, 26, v6
	v_add_u32_e32 v7, v0, v6
	v_ashrrev_i32_e32 v6, 6, v7
	v_and_b32_e32 v7, 0xc0, v7
	v_sub_u32_e32 v0, v0, v7
	v_ashrrev_i16_sdwa v0, v203, sext(v0) dst_sel:DWORD dst_unused:UNUSED_PAD src0_sel:DWORD src1_sel:BYTE_0
	v_bfe_i32 v7, v0, 0, 16
	s_ashr_i32 s0, s36, 6
	v_add_u32_e32 v0, v8, v7
	v_lshlrev_b32_e32 v8, 3, v5
	s_lshl_b32 s54, s0, 10
	v_and_b32_e32 v8, 0xffff0, v8
	v_add_lshl_u32 v8, v6, v8, 12
	s_add_i32 s55, s54, 0
	v_readlane_b32 s12, v253, 8
	v_lshl_add_u32 v0, v0, 1, v8
	s_add_i32 m0, s55, 0x10000
	v_readlane_b32 s13, v253, 9
	s_add_i32 s56, s55, 0x2000
	s_add_i32 s57, s55, 0x4000
	s_add_i32 s58, s55, 0x6000
	s_ashr_i32 s1, s36, 8
	s_nop 0
	global_load_lds_dwordx4 v0, s[12:13]
	s_add_i32 m0, s55, 0x12000
	s_nop 0
	global_load_lds_dwordx4 v130, s[12:13]
	v_readlane_b32 s12, v253, 4
	s_mov_b32 m0, s55
	v_readlane_b32 s13, v253, 5
	s_nop 4
	global_load_lds_dwordx4 v0, s[12:13]
	s_mov_b32 m0, s56
	s_nop 0
	global_load_lds_dwordx4 v130, s[12:13]
	v_readlane_b32 s12, v253, 2
	s_add_i32 m0, s55, 0x14000
	v_readlane_b32 s13, v253, 3
	s_nop 4
	global_load_lds_dwordx4 v0, s[12:13]
	s_add_i32 m0, s55, 0x16000
	s_cmp_lg_u32 s1, 1
	global_load_lds_dwordx4 v130, s[12:13]
	v_readlane_b32 s12, v253, 6
	s_mov_b32 m0, s57
	v_readlane_b32 s13, v253, 7
	s_nop 4
	global_load_lds_dwordx4 v0, s[12:13]
	s_mov_b32 m0, s58
	s_nop 0
	global_load_lds_dwordx4 v130, s[12:13]
	s_cbranch_scc1 .LBB0_267
	s_barrier
	s_setprio 1

.LBB0_282:
	s_add_i32 s67, s50, 2
	s_add_u32 s51, s0, 0xfff80080
	s_addc_u32 s52, s1, -1
	s_add_i32 s68, 0, 0x10000
	v_add_u32_e32 v148, s68, v153
	ds_read_b128 v[136:139], v148
	ds_read_b128 v[140:143], v148 offset:1024
	ds_read_b128 v[144:147], v148 offset:2048
	ds_read_b128 v[148:151], v148 offset:3072
	s_cmp_eq_u32 s12, s50
	s_cselect_b32 s50, s48, s13
	s_cselect_b32 s53, s47, s52
	s_cselect_b32 s52, s46, s51
	s_cselect_b32 s51, s49, s66
	v_lshl_add_u64 v[156:157], s[0:1], 0, v[132:133]
	s_add_i32 m0, s55, 0xc000
	ds_read_b128 v[168:171], v155
	ds_read_b128 v[172:175], v155 offset:1024
	ds_read_b128 v[176:179], v155 offset:2048
	ds_read_b128 v[180:183], v155 offset:3072
	ds_read_b128 v[184:187], v155 offset:4096
	ds_read_b128 v[188:191], v155 offset:5120
	ds_read_b128 v[192:195], v155 offset:6144
	ds_read_b128 v[196:199], v155 offset:7168
	global_load_lds_dwordx4 v[156:157], off
	v_lshl_add_u64 v[156:157], s[0:1], 0, v[134:135]
	s_add_i32 m0, s55, 0xe000
	s_nop 0
	global_load_lds_dwordx4 v[156:157], off
	s_waitcnt lgkmcnt(8)
	s_barrier
	s_waitcnt lgkmcnt(0)
	s_waitcnt lgkmcnt(0)
	v_mfma_f32_16x16x32_bf16 v[126:129], v[136:139], v[168:171], v[126:129]
	v_mfma_f32_16x16x32_bf16 v[122:125], v[144:147], v[168:171], v[122:125]
	v_mfma_f32_16x16x32_bf16 v[110:113], v[136:139], v[176:179], v[110:113]
	v_mfma_f32_16x16x32_bf16 v[106:109], v[144:147], v[176:179], v[106:109]
	v_mfma_f32_16x16x32_bf16 v[94:97], v[136:139], v[184:187], v[94:97]
	v_mfma_f32_16x16x32_bf16 v[90:93], v[144:147], v[184:187], v[90:93]
	v_mfma_f32_16x16x32_bf16 v[78:81], v[136:139], v[192:195], v[78:81]
	v_mfma_f32_16x16x32_bf16 v[74:77], v[144:147], v[192:195], v[74:77]
	v_mfma_f32_16x16x32_bf16 v[126:129], v[140:143], v[172:175], v[126:129]
	v_mfma_f32_16x16x32_bf16 v[122:125], v[148:151], v[172:175], v[122:125]
	v_mfma_f32_16x16x32_bf16 v[110:113], v[140:143], v[180:183], v[110:113]
	v_mfma_f32_16x16x32_bf16 v[106:109], v[148:151], v[180:183], v[106:109]
	v_mfma_f32_16x16x32_bf16 v[94:97], v[140:143], v[188:191], v[94:97]
	v_mfma_f32_16x16x32_bf16 v[90:93], v[148:151], v[188:191], v[90:93]
	v_mfma_f32_16x16x32_bf16 v[78:81], v[140:143], v[196:199], v[78:81]
	v_mfma_f32_16x16x32_bf16 v[74:77], v[148:151], v[196:199], v[74:77]
	s_barrier
	s_add_i32 s70, 0, 0x14000
	v_add_u32_e32 v156, s70, v153
	s_add_i32 s68, s68, s54
	ds_read_b128 v[224:227], v156
	ds_read_b128 v[228:231], v156 offset:1024
	ds_read_b128 v[232:235], v156 offset:2048
	ds_read_b128 v[236:239], v156 offset:3072
	v_lshl_add_u64 v[156:157], s[50:51], 0, v[0:1]
	s_mov_b32 m0, s68
	v_lshl_add_u64 v[200:201], s[50:51], 0, v[130:131]
	global_load_lds_dwordx4 v[156:157], off
	s_add_i32 m0, s68, 0x2000
	s_nop 0
	global_load_lds_dwordx4 v[200:201], off
	s_barrier
	s_waitcnt lgkmcnt(0)
	s_waitcnt lgkmcnt(0)
	v_mfma_f32_16x16x32_bf16 v[118:121], v[224:227], v[168:171], v[118:121]
	v_mfma_f32_16x16x32_bf16 v[114:117], v[232:235], v[168:171], v[114:117]
	v_mfma_f32_16x16x32_bf16 v[102:105], v[224:227], v[176:179], v[102:105]
	v_mfma_f32_16x16x32_bf16 v[98:101], v[232:235], v[176:179], v[98:101]
	v_mfma_f32_16x16x32_bf16 v[86:89], v[224:227], v[184:187], v[86:89]
	v_mfma_f32_16x16x32_bf16 v[82:85], v[232:235], v[184:187], v[82:85]
	v_mfma_f32_16x16x32_bf16 v[70:73], v[224:227], v[192:195], v[70:73]
	v_mfma_f32_16x16x32_bf16 v[66:69], v[232:235], v[192:195], v[66:69]
	v_mfma_f32_16x16x32_bf16 v[118:121], v[228:231], v[172:175], v[118:121]
	v_mfma_f32_16x16x32_bf16 v[114:117], v[236:239], v[172:175], v[114:117]
	v_mfma_f32_16x16x32_bf16 v[102:105], v[228:231], v[180:183], v[102:105]
	v_mfma_f32_16x16x32_bf16 v[98:101], v[236:239], v[180:183], v[98:101]
	v_mfma_f32_16x16x32_bf16 v[86:89], v[228:231], v[188:191], v[86:89]
	v_mfma_f32_16x16x32_bf16 v[82:85], v[236:239], v[188:191], v[82:85]
	v_mfma_f32_16x16x32_bf16 v[70:73], v[228:231], v[196:199], v[70:73]
	v_mfma_f32_16x16x32_bf16 v[66:69], v[236:239], v[196:199], v[66:69]
	s_mov_b32 m0, s55
	v_lshl_add_u64 v[210:211], s[52:53], 0, v[0:1]
	s_barrier
	ds_read_b128 v[168:171], v155 offset:16384
	ds_read_b128 v[172:175], v155 offset:17408
	ds_read_b128 v[176:179], v155 offset:18432
	ds_read_b128 v[180:183], v155 offset:19456
	ds_read_b128 v[184:187], v155 offset:20480
	ds_read_b128 v[188:191], v155 offset:21504
	ds_read_b128 v[192:195], v155 offset:22528
	ds_read_b128 v[196:199], v155 offset:23552
	global_load_lds_dwordx4 v[210:211], off
	v_lshl_add_u64 v[212:213], s[52:53], 0, v[130:131]
	s_mov_b32 m0, s56
	s_nop 0
	global_load_lds_dwordx4 v[212:213], off
	s_barrier
	s_waitcnt lgkmcnt(0)
	s_waitcnt lgkmcnt(0)
	v_mfma_f32_16x16x32_bf16 v[62:65], v[136:139], v[168:171], v[62:65]
	v_mfma_f32_16x16x32_bf16 v[58:61], v[144:147], v[168:171], v[58:61]
	v_mfma_f32_16x16x32_bf16 v[46:49], v[136:139], v[176:179], v[46:49]
	v_mfma_f32_16x16x32_bf16 v[42:45], v[144:147], v[176:179], v[42:45]
	v_mfma_f32_16x16x32_bf16 v[30:33], v[136:139], v[184:187], v[30:33]
	v_mfma_f32_16x16x32_bf16 v[26:29], v[144:147], v[184:187], v[26:29]
	v_mfma_f32_16x16x32_bf16 v[14:17], v[136:139], v[192:195], v[14:17]
	v_mfma_f32_16x16x32_bf16 v[10:13], v[144:147], v[192:195], v[10:13]
	v_mfma_f32_16x16x32_bf16 v[62:65], v[140:143], v[172:175], v[62:65]
	v_mfma_f32_16x16x32_bf16 v[58:61], v[148:151], v[172:175], v[58:61]
	v_mfma_f32_16x16x32_bf16 v[46:49], v[140:143], v[180:183], v[46:49]
	v_mfma_f32_16x16x32_bf16 v[42:45], v[148:151], v[180:183], v[42:45]
	v_mfma_f32_16x16x32_bf16 v[30:33], v[140:143], v[188:191], v[30:33]
	v_mfma_f32_16x16x32_bf16 v[26:29], v[148:151], v[188:191], v[26:29]
	v_mfma_f32_16x16x32_bf16 v[14:17], v[140:143], v[196:199], v[14:17]
	v_mfma_f32_16x16x32_bf16 v[10:13], v[148:151], v[196:199], v[10:13]
	s_barrier
	s_add_u32 s68, s50, 0x80000
	s_addc_u32 s69, s51, 0
	s_add_i32 s70, s70, s54
	v_lshl_add_u64 v[136:137], s[68:69], 0, v[0:1]
	s_mov_b32 m0, s70
	s_nop 0
	global_load_lds_dwordx4 v[136:137], off
	v_lshl_add_u64 v[136:137], s[68:69], 0, v[130:131]
	s_add_i32 m0, s70, 0x2000
	s_nop 0
	global_load_lds_dwordx4 v[136:137], off
	s_waitcnt vmcnt(6)
	s_barrier
	v_mfma_f32_16x16x32_bf16 v[54:57], v[224:227], v[168:171], v[54:57]
	v_mfma_f32_16x16x32_bf16 v[50:53], v[232:235], v[168:171], v[50:53]
	v_mfma_f32_16x16x32_bf16 v[38:41], v[224:227], v[176:179], v[38:41]
	v_mfma_f32_16x16x32_bf16 v[34:37], v[232:235], v[176:179], v[34:37]
	v_mfma_f32_16x16x32_bf16 v[22:25], v[224:227], v[184:187], v[22:25]
	v_mfma_f32_16x16x32_bf16 v[18:21], v[232:235], v[184:187], v[18:21]
	v_mfma_f32_16x16x32_bf16 v[6:9], v[224:227], v[192:195], v[6:9]
	v_mfma_f32_16x16x32_bf16 v[2:5], v[232:235], v[192:195], v[2:5]
	v_mfma_f32_16x16x32_bf16 v[54:57], v[228:231], v[172:175], v[54:57]
	v_mfma_f32_16x16x32_bf16 v[50:53], v[236:239], v[172:175], v[50:53]
	v_mfma_f32_16x16x32_bf16 v[38:41], v[228:231], v[180:183], v[38:41]
	v_mfma_f32_16x16x32_bf16 v[34:37], v[236:239], v[180:183], v[34:37]
	v_mfma_f32_16x16x32_bf16 v[22:25], v[228:231], v[188:191], v[22:25]
	v_mfma_f32_16x16x32_bf16 v[18:21], v[236:239], v[188:191], v[18:21]
	v_mfma_f32_16x16x32_bf16 v[6:9], v[228:231], v[196:199], v[6:9]
	v_mfma_f32_16x16x32_bf16 v[2:5], v[236:239], v[196:199], v[2:5]
	s_add_i32 s68, 0, 0x18000
	v_add_u32_e32 v148, s68, v153
	s_barrier
	ds_read_b128 v[136:139], v148
	ds_read_b128 v[140:143], v148 offset:1024
	ds_read_b128 v[144:147], v148 offset:2048
	ds_read_b128 v[148:151], v148 offset:3072
	s_add_u32 s52, s52, 0x80000
	s_addc_u32 s53, s53, 0
	s_mov_b32 m0, s57
	v_lshl_add_u64 v[220:221], s[52:53], 0, v[0:1]
	ds_read_b128 v[168:171], v155 offset:32768
	ds_read_b128 v[172:175], v155 offset:33792
	ds_read_b128 v[176:179], v155 offset:34816
	ds_read_b128 v[180:183], v155 offset:35840
	ds_read_b128 v[184:187], v155 offset:36864
	ds_read_b128 v[188:191], v155 offset:37888
	ds_read_b128 v[192:195], v155 offset:38912
	ds_read_b128 v[196:199], v155 offset:39936
	global_load_lds_dwordx4 v[220:221], off
	v_lshl_add_u64 v[220:221], s[52:53], 0, v[130:131]
	s_mov_b32 m0, s58
	s_nop 0
	global_load_lds_dwordx4 v[220:221], off
	s_waitcnt lgkmcnt(8)
	s_barrier
	s_waitcnt lgkmcnt(0)
	s_waitcnt lgkmcnt(0)
	v_mfma_f32_16x16x32_bf16 v[126:129], v[136:139], v[168:171], v[126:129]
	v_mfma_f32_16x16x32_bf16 v[122:125], v[144:147], v[168:171], v[122:125]
	v_mfma_f32_16x16x32_bf16 v[110:113], v[136:139], v[176:179], v[110:113]
	v_mfma_f32_16x16x32_bf16 v[106:109], v[144:147], v[176:179], v[106:109]
	v_mfma_f32_16x16x32_bf16 v[94:97], v[136:139], v[184:187], v[94:97]
	v_mfma_f32_16x16x32_bf16 v[90:93], v[144:147], v[184:187], v[90:93]
	v_mfma_f32_16x16x32_bf16 v[78:81], v[136:139], v[192:195], v[78:81]
	v_mfma_f32_16x16x32_bf16 v[74:77], v[144:147], v[192:195], v[74:77]
	v_mfma_f32_16x16x32_bf16 v[126:129], v[140:143], v[172:175], v[126:129]
	v_mfma_f32_16x16x32_bf16 v[122:125], v[148:151], v[172:175], v[122:125]
	v_mfma_f32_16x16x32_bf16 v[110:113], v[140:143], v[180:183], v[110:113]
	v_mfma_f32_16x16x32_bf16 v[106:109], v[148:151], v[180:183], v[106:109]
	v_mfma_f32_16x16x32_bf16 v[94:97], v[140:143], v[188:191], v[94:97]
	v_mfma_f32_16x16x32_bf16 v[90:93], v[148:151], v[188:191], v[90:93]
	v_mfma_f32_16x16x32_bf16 v[78:81], v[140:143], v[196:199], v[78:81]
	v_mfma_f32_16x16x32_bf16 v[74:77], v[148:151], v[196:199], v[74:77]
	s_barrier
	s_add_i32 s52, 0, 0x1c000
	s_add_i32 s53, s68, s54
	v_add_u32_e32 v161, s52, v153
	v_lshl_add_u64 v[156:157], v[156:157], 0, s[94:95]
	s_mov_b32 m0, s53
	ds_read_b128 v[224:227], v161
	ds_read_b128 v[228:231], v161 offset:1024
	ds_read_b128 v[232:235], v161 offset:2048
	ds_read_b128 v[236:239], v161 offset:3072
	global_load_lds_dwordx4 v[156:157], off
	v_lshl_add_u64 v[156:157], v[200:201], 0, s[94:95]
	s_add_i32 m0, s53, 0x2000
	s_nop 0
	global_load_lds_dwordx4 v[156:157], off
	s_barrier
	s_waitcnt lgkmcnt(0)
	s_waitcnt lgkmcnt(0)
	v_mfma_f32_16x16x32_bf16 v[118:121], v[224:227], v[168:171], v[118:121]
	v_mfma_f32_16x16x32_bf16 v[114:117], v[232:235], v[168:171], v[114:117]
	v_mfma_f32_16x16x32_bf16 v[102:105], v[224:227], v[176:179], v[102:105]
	v_mfma_f32_16x16x32_bf16 v[98:101], v[232:235], v[176:179], v[98:101]
	v_mfma_f32_16x16x32_bf16 v[86:89], v[224:227], v[184:187], v[86:89]
	v_mfma_f32_16x16x32_bf16 v[82:85], v[232:235], v[184:187], v[82:85]
	v_mfma_f32_16x16x32_bf16 v[70:73], v[224:227], v[192:195], v[70:73]
	v_mfma_f32_16x16x32_bf16 v[66:69], v[232:235], v[192:195], v[66:69]
	v_mfma_f32_16x16x32_bf16 v[118:121], v[228:231], v[172:175], v[118:121]
	v_mfma_f32_16x16x32_bf16 v[114:117], v[236:239], v[172:175], v[114:117]
	v_mfma_f32_16x16x32_bf16 v[102:105], v[228:231], v[180:183], v[102:105]
	v_mfma_f32_16x16x32_bf16 v[98:101], v[236:239], v[180:183], v[98:101]
	v_mfma_f32_16x16x32_bf16 v[86:89], v[228:231], v[188:191], v[86:89]
	v_mfma_f32_16x16x32_bf16 v[82:85], v[236:239], v[188:191], v[82:85]
	v_mfma_f32_16x16x32_bf16 v[70:73], v[228:231], v[196:199], v[70:73]
	v_mfma_f32_16x16x32_bf16 v[66:69], v[236:239], v[196:199], v[66:69]
	s_mov_b32 m0, s59
	v_lshl_add_u64 v[156:157], v[210:211], 0, s[94:95]
	s_barrier
	ds_read_b128 v[168:171], v155 offset:49152
	ds_read_b128 v[172:175], v155 offset:50176
	ds_read_b128 v[176:179], v155 offset:51200
	ds_read_b128 v[180:183], v155 offset:52224
	ds_read_b128 v[184:187], v155 offset:53248
	ds_read_b128 v[188:191], v155 offset:54272
	ds_read_b128 v[192:195], v155 offset:55296
	ds_read_b128 v[196:199], v155 offset:56320
	global_load_lds_dwordx4 v[156:157], off
	v_lshl_add_u64 v[156:157], v[212:213], 0, s[94:95]
	s_mov_b32 m0, s60
	s_nop 0
	global_load_lds_dwordx4 v[156:157], off
	s_barrier
	s_waitcnt lgkmcnt(0)
	s_waitcnt lgkmcnt(0)
	v_mfma_f32_16x16x32_bf16 v[62:65], v[136:139], v[168:171], v[62:65]
	v_mfma_f32_16x16x32_bf16 v[58:61], v[144:147], v[168:171], v[58:61]
	v_mfma_f32_16x16x32_bf16 v[46:49], v[136:139], v[176:179], v[46:49]
	v_mfma_f32_16x16x32_bf16 v[42:45], v[144:147], v[176:179], v[42:45]
	v_mfma_f32_16x16x32_bf16 v[30:33], v[136:139], v[184:187], v[30:33]
	v_mfma_f32_16x16x32_bf16 v[26:29], v[144:147], v[184:187], v[26:29]
	v_mfma_f32_16x16x32_bf16 v[14:17], v[136:139], v[192:195], v[14:17]
	v_mfma_f32_16x16x32_bf16 v[10:13], v[144:147], v[192:195], v[10:13]
	v_mfma_f32_16x16x32_bf16 v[62:65], v[140:143], v[172:175], v[62:65]
	v_mfma_f32_16x16x32_bf16 v[58:61], v[148:151], v[172:175], v[58:61]
	v_mfma_f32_16x16x32_bf16 v[46:49], v[140:143], v[180:183], v[46:49]
	v_mfma_f32_16x16x32_bf16 v[42:45], v[148:151], v[180:183], v[42:45]
	v_mfma_f32_16x16x32_bf16 v[30:33], v[140:143], v[188:191], v[30:33]
	v_mfma_f32_16x16x32_bf16 v[26:29], v[148:151], v[188:191], v[26:29]
	v_mfma_f32_16x16x32_bf16 v[14:17], v[140:143], v[196:199], v[14:17]
	v_mfma_f32_16x16x32_bf16 v[10:13], v[148:151], v[196:199], v[10:13]
	s_barrier
	s_add_u32 s50, s50, 0x80080
	s_addc_u32 s51, s51, 0
	s_add_i32 s52, s52, s54
	v_lshl_add_u64 v[136:137], s[50:51], 0, v[0:1]
	s_mov_b32 m0, s52
	s_nop 0
	global_load_lds_dwordx4 v[136:137], off
	v_lshl_add_u64 v[136:137], s[50:51], 0, v[130:131]
	s_add_i32 m0, s52, 0x2000
	s_nop 0
	global_load_lds_dwordx4 v[136:137], off
	s_waitcnt vmcnt(6)
	s_barrier
	v_mfma_f32_16x16x32_bf16 v[54:57], v[224:227], v[168:171], v[54:57]
	v_mfma_f32_16x16x32_bf16 v[50:53], v[232:235], v[168:171], v[50:53]
	v_mfma_f32_16x16x32_bf16 v[38:41], v[224:227], v[176:179], v[38:41]
	v_mfma_f32_16x16x32_bf16 v[34:37], v[232:235], v[176:179], v[34:37]
	v_mfma_f32_16x16x32_bf16 v[22:25], v[224:227], v[184:187], v[22:25]
	v_mfma_f32_16x16x32_bf16 v[18:21], v[232:235], v[184:187], v[18:21]
	v_mfma_f32_16x16x32_bf16 v[6:9], v[224:227], v[192:195], v[6:9]
	v_mfma_f32_16x16x32_bf16 v[2:5], v[232:235], v[192:195], v[2:5]
	v_mfma_f32_16x16x32_bf16 v[54:57], v[228:231], v[172:175], v[54:57]
	v_mfma_f32_16x16x32_bf16 v[50:53], v[236:239], v[172:175], v[50:53]
	v_mfma_f32_16x16x32_bf16 v[38:41], v[228:231], v[180:183], v[38:41]
	v_mfma_f32_16x16x32_bf16 v[34:37], v[236:239], v[180:183], v[34:37]
	v_mfma_f32_16x16x32_bf16 v[22:25], v[228:231], v[188:191], v[22:25]
	v_mfma_f32_16x16x32_bf16 v[18:21], v[236:239], v[188:191], v[18:21]
	v_mfma_f32_16x16x32_bf16 v[6:9], v[228:231], v[196:199], v[6:9]
	v_mfma_f32_16x16x32_bf16 v[2:5], v[236:239], v[196:199], v[2:5]
	s_add_u32 s0, s0, 0x100
	s_addc_u32 s1, s1, 0
	s_add_u32 s13, s13, 0x100
	s_addc_u32 s66, s66, 0
	s_cmp_ge_i32 s67, s41
	s_mov_b32 s50, s67
	s_barrier
	s_cbranch_scc0 .LBB0_282
	s_cmp_eq_u32 s63, 2
	s_cbranch_scc1 .Lepi6_orig
	v_readlane_b32 s90, v255, 17
	v_readlane_b32 s91, v255, 18
	v_readlane_b32 s96, v255, 19
	v_readlane_b32 s97, v255, 20
	v_readlane_b32 s8, v255, 25
	v_readlane_b32 s9, v255, 26
	v_readlane_b32 s68, v253, 58
	v_readlane_b32 s69, v253, 59
	v_lshl_or_b32 v156, s64, 8, v154
	v_lshlrev_b32_e32 v156, 2, v156
	v_lshl_add_u32 v157, v152, 13, v156
	s_lshl_b32 s72, s65, 21
	s_add_u32 s74, s68, s72
	s_addc_u32 s75, s69, 0
	s_add_u32 s76, s22, s72
	s_addc_u32 s77, s23, 0
	s_lshr_b32 s73, s65, 3
	s_mul_i32 s73, s73, 0xc000
	s_add_u32 s73, s73, 0x4000
	s_add_u32 s70, s90, s73
	s_addc_u32 s71, s91, 0
	global_load_dwordx4 v[140:143], v156, s[70:71]
	global_load_dwordx4 v[144:147], v156, s[70:71] offset:64
	global_load_dwordx4 v[148:151], v156, s[70:71] offset:512
	global_load_dwordx4 v[168:171], v156, s[70:71] offset:576
	global_load_dwordx4 v[224:227], v157, s[74:75] nt
	global_load_dwordx4 v[228:231], v157, s[74:75] offset:64 nt
	global_load_dwordx4 v[232:235], v157, s[74:75] offset:512 nt
	global_load_dwordx4 v[236:239], v157, s[74:75] offset:576 nt
	s_add_u32 s74, s74, 0x20000
	s_addc_u32 s75, s75, 0
	global_load_dwordx4 v[240:243], v157, s[74:75] nt
	global_load_dwordx4 v[244:247], v157, s[74:75] offset:64 nt
	s_waitcnt vmcnt(5)
	v_pk_fma_f32 v[128:129], v[128:129], v[142:143], v[226:227]
	v_pk_fma_f32 v[126:127], v[126:127], v[140:141], v[224:225]
	global_store_dwordx4 v157, v[126:129], s[76:77]
	global_load_dwordx4 v[224:227], v157, s[74:75] offset:512 nt
	s_waitcnt vmcnt(6)
	v_pk_fma_f32 v[124:125], v[124:125], v[146:147], v[230:231]
	v_pk_fma_f32 v[122:123], v[122:123], v[144:145], v[228:229]
	global_store_dwordx4 v157, v[122:125], s[76:77] offset:64
	global_load_dwordx4 v[228:231], v157, s[74:75] offset:576 nt
	s_waitcnt vmcnt(7)
	v_pk_fma_f32 v[120:121], v[120:121], v[150:151], v[234:235]
	v_pk_fma_f32 v[118:119], v[118:119], v[148:149], v[232:233]
	global_store_dwordx4 v157, v[118:121], s[76:77] offset:512
	s_add_u32 s74, s74, 0x20000
	s_addc_u32 s75, s75, 0
	global_load_dwordx4 v[232:235], v157, s[74:75] nt
	s_waitcnt vmcnt(8)
	v_pk_fma_f32 v[116:117], v[116:117], v[170:171], v[238:239]
	v_pk_fma_f32 v[114:115], v[114:115], v[168:169], v[236:237]
	global_store_dwordx4 v157, v[114:117], s[76:77] offset:576
	global_load_dwordx4 v[236:239], v157, s[74:75] offset:64 nt
	s_add_u32 s76, s76, 0x20000
	s_addc_u32 s77, s77, 0
	s_waitcnt vmcnt(9)
	v_pk_fma_f32 v[112:113], v[112:113], v[142:143], v[242:243]
	v_pk_fma_f32 v[110:111], v[110:111], v[140:141], v[240:241]
	global_store_dwordx4 v157, v[110:113], s[76:77]
	global_load_dwordx4 v[240:243], v157, s[74:75] offset:512 nt
	s_waitcnt vmcnt(10)
	v_pk_fma_f32 v[108:109], v[108:109], v[146:147], v[246:247]
	v_pk_fma_f32 v[106:107], v[106:107], v[144:145], v[244:245]
	global_store_dwordx4 v157, v[106:109], s[76:77] offset:64
	global_load_dwordx4 v[244:247], v157, s[74:75] offset:576 nt
	s_waitcnt vmcnt(10)
	v_pk_fma_f32 v[104:105], v[104:105], v[150:151], v[226:227]
	v_pk_fma_f32 v[102:103], v[102:103], v[148:149], v[224:225]
	global_store_dwordx4 v157, v[102:105], s[76:77] offset:512
	s_add_u32 s74, s74, 0x20000
	s_addc_u32 s75, s75, 0
	global_load_dwordx4 v[224:227], v157, s[74:75] nt
	s_waitcnt vmcnt(10)
	v_pk_fma_f32 v[100:101], v[100:101], v[170:171], v[230:231]
	v_pk_fma_f32 v[98:99], v[98:99], v[168:169], v[228:229]
	global_store_dwordx4 v157, v[98:101], s[76:77] offset:576
	global_load_dwordx4 v[228:231], v157, s[74:75] offset:64 nt
	s_add_u32 s76, s76, 0x20000
	s_addc_u32 s77, s77, 0
	s_waitcnt vmcnt(10)
	v_pk_fma_f32 v[96:97], v[96:97], v[142:143], v[234:235]
	v_pk_fma_f32 v[94:95], v[94:95], v[140:141], v[232:233]
	global_store_dwordx4 v157, v[94:97], s[76:77]
	global_load_dwordx4 v[232:235], v157, s[74:75] offset:512 nt
	s_waitcnt vmcnt(10)
	v_pk_fma_f32 v[92:93], v[92:93], v[146:147], v[238:239]
	v_pk_fma_f32 v[90:91], v[90:91], v[144:145], v[236:237]
	global_store_dwordx4 v157, v[90:93], s[76:77] offset:64
	global_load_dwordx4 v[236:239], v157, s[74:75] offset:576 nt
	s_waitcnt vmcnt(10)
	v_pk_fma_f32 v[88:89], v[88:89], v[150:151], v[242:243]
	v_pk_fma_f32 v[86:87], v[86:87], v[148:149], v[240:241]
	global_store_dwordx4 v157, v[86:89], s[76:77] offset:512
	s_add_u32 s74, s74, 0xa0000
	s_addc_u32 s75, s75, 0
	global_load_dwordx4 v[240:243], v157, s[74:75] nt
	s_waitcnt vmcnt(10)
	v_pk_fma_f32 v[84:85], v[84:85], v[170:171], v[246:247]
	v_pk_fma_f32 v[82:83], v[82:83], v[168:169], v[244:245]
	global_store_dwordx4 v157, v[82:85], s[76:77] offset:576
	global_load_dwordx4 v[244:247], v157, s[74:75] offset:64 nt
	s_add_u32 s76, s76, 0x20000
	s_addc_u32 s77, s77, 0
	s_waitcnt vmcnt(10)
	v_pk_fma_f32 v[80:81], v[80:81], v[142:143], v[226:227]
	v_pk_fma_f32 v[78:79], v[78:79], v[140:141], v[224:225]
	global_store_dwordx4 v157, v[78:81], s[76:77]
	global_load_dwordx4 v[224:227], v157, s[74:75] offset:512 nt
	s_waitcnt vmcnt(10)
	v_pk_fma_f32 v[76:77], v[76:77], v[146:147], v[230:231]
	v_pk_fma_f32 v[74:75], v[74:75], v[144:145], v[228:229]
	global_store_dwordx4 v157, v[74:77], s[76:77] offset:64
	global_load_dwordx4 v[228:231], v157, s[74:75] offset:576 nt
	s_waitcnt vmcnt(10)
	v_pk_fma_f32 v[72:73], v[72:73], v[150:151], v[234:235]
	v_pk_fma_f32 v[70:71], v[70:71], v[148:149], v[232:233]
	global_store_dwordx4 v157, v[70:73], s[76:77] offset:512
	s_add_u32 s74, s74, 0x20000
	s_addc_u32 s75, s75, 0
	global_load_dwordx4 v[232:235], v157, s[74:75] nt
	s_waitcnt vmcnt(10)
	v_pk_fma_f32 v[68:69], v[68:69], v[170:171], v[238:239]
	v_pk_fma_f32 v[66:67], v[66:67], v[168:169], v[236:237]
	global_store_dwordx4 v157, v[66:69], s[76:77] offset:576
	global_load_dwordx4 v[236:239], v157, s[74:75] offset:64 nt
	s_add_u32 s76, s76, 0xa0000
	s_addc_u32 s77, s77, 0
	s_waitcnt vmcnt(10)
	v_pk_fma_f32 v[64:65], v[64:65], v[142:143], v[242:243]
	v_pk_fma_f32 v[62:63], v[62:63], v[140:141], v[240:241]
	global_store_dwordx4 v157, v[62:65], s[76:77]
	global_load_dwordx4 v[240:243], v157, s[74:75] offset:512 nt
	s_waitcnt vmcnt(10)
	v_pk_fma_f32 v[60:61], v[60:61], v[146:147], v[246:247]
	v_pk_fma_f32 v[58:59], v[58:59], v[144:145], v[244:245]
	global_store_dwordx4 v157, v[58:61], s[76:77] offset:64
	global_load_dwordx4 v[244:247], v157, s[74:75] offset:576 nt
	s_waitcnt vmcnt(10)
	v_pk_fma_f32 v[56:57], v[56:57], v[150:151], v[226:227]
	v_pk_fma_f32 v[54:55], v[54:55], v[148:149], v[224:225]
	global_store_dwordx4 v157, v[54:57], s[76:77] offset:512
	s_add_u32 s74, s74, 0x20000
	s_addc_u32 s75, s75, 0
	global_load_dwordx4 v[224:227], v157, s[74:75] nt
	s_waitcnt vmcnt(10)
	v_pk_fma_f32 v[52:53], v[52:53], v[170:171], v[230:231]
	v_pk_fma_f32 v[50:51], v[50:51], v[168:169], v[228:229]
	global_store_dwordx4 v157, v[50:53], s[76:77] offset:576
	global_load_dwordx4 v[228:231], v157, s[74:75] offset:64 nt
	s_add_u32 s76, s76, 0x20000
	s_addc_u32 s77, s77, 0
	s_waitcnt vmcnt(10)
	v_pk_fma_f32 v[48:49], v[48:49], v[142:143], v[234:235]
	v_pk_fma_f32 v[46:47], v[46:47], v[140:141], v[232:233]
	global_store_dwordx4 v157, v[46:49], s[76:77]
	global_load_dwordx4 v[232:235], v157, s[74:75] offset:512 nt
	s_waitcnt vmcnt(10)
	v_pk_fma_f32 v[44:45], v[44:45], v[146:147], v[238:239]
	v_pk_fma_f32 v[42:43], v[42:43], v[144:145], v[236:237]
	global_store_dwordx4 v157, v[42:45], s[76:77] offset:64
	global_load_dwordx4 v[236:239], v157, s[74:75] offset:576 nt
	s_waitcnt vmcnt(10)
	v_pk_fma_f32 v[40:41], v[40:41], v[150:151], v[242:243]
	v_pk_fma_f32 v[38:39], v[38:39], v[148:149], v[240:241]
	global_store_dwordx4 v157, v[38:41], s[76:77] offset:512
	s_add_u32 s74, s74, 0x20000
	s_addc_u32 s75, s75, 0
	global_load_dwordx4 v[240:243], v157, s[74:75] nt
	s_waitcnt vmcnt(10)
	v_pk_fma_f32 v[36:37], v[36:37], v[170:171], v[246:247]
	v_pk_fma_f32 v[34:35], v[34:35], v[168:169], v[244:245]
	global_store_dwordx4 v157, v[34:37], s[76:77] offset:576
	global_load_dwordx4 v[244:247], v157, s[74:75] offset:64 nt
	s_add_u32 s76, s76, 0x20000
	s_addc_u32 s77, s77, 0
	s_waitcnt vmcnt(10)
	v_pk_fma_f32 v[32:33], v[32:33], v[142:143], v[226:227]
	v_pk_fma_f32 v[30:31], v[30:31], v[140:141], v[224:225]
	global_store_dwordx4 v157, v[30:33], s[76:77]
	global_load_dwordx4 v[224:227], v157, s[74:75] offset:512 nt
	s_waitcnt vmcnt(10)
	v_pk_fma_f32 v[28:29], v[28:29], v[146:147], v[230:231]
	v_pk_fma_f32 v[26:27], v[26:27], v[144:145], v[228:229]
	global_store_dwordx4 v157, v[26:29], s[76:77] offset:64
	global_load_dwordx4 v[228:231], v157, s[74:75] offset:576 nt
	s_waitcnt vmcnt(10)
	v_pk_fma_f32 v[24:25], v[24:25], v[150:151], v[234:235]
	v_pk_fma_f32 v[22:23], v[22:23], v[148:149], v[232:233]
	global_store_dwordx4 v157, v[22:25], s[76:77] offset:512
	s_waitcnt vmcnt(9)
	v_pk_fma_f32 v[20:21], v[20:21], v[170:171], v[238:239]
	v_pk_fma_f32 v[18:19], v[18:19], v[168:169], v[236:237]
	global_store_dwordx4 v157, v[18:21], s[76:77] offset:576
	s_add_u32 s76, s76, 0x20000
	s_addc_u32 s77, s77, 0
	s_waitcnt vmcnt(8)
	v_pk_fma_f32 v[16:17], v[16:17], v[142:143], v[242:243]
	v_pk_fma_f32 v[14:15], v[14:15], v[140:141], v[240:241]
	global_store_dwordx4 v157, v[14:17], s[76:77]
	s_waitcnt vmcnt(7)
	v_pk_fma_f32 v[12:13], v[12:13], v[146:147], v[246:247]
	v_pk_fma_f32 v[10:11], v[10:11], v[144:145], v[244:245]
	global_store_dwordx4 v157, v[10:13], s[76:77] offset:64
	s_waitcnt vmcnt(6)
	v_pk_fma_f32 v[8:9], v[8:9], v[150:151], v[226:227]
	v_pk_fma_f32 v[6:7], v[6:7], v[148:149], v[224:225]
	global_store_dwordx4 v157, v[6:9], s[76:77] offset:512
	s_waitcnt vmcnt(5)
	v_pk_fma_f32 v[4:5], v[4:5], v[170:171], v[230:231]
	v_pk_fma_f32 v[2:3], v[2:3], v[168:169], v[228:229]
	global_store_dwordx4 v157, v[2:5], s[76:77] offset:576
	s_branch .LBB0_269

.LBB0_560:
	v_ashrrev_i32_e32 v0, 31, v166
	v_lshrrev_b32_e32 v0, 26, v0
	v_add_u32_e32 v0, v166, v0
	s_waitcnt vmcnt(0)
	v_ashrrev_i32_e32 v2, 6, v0
	v_bfe_i32 v0, v166, 27, 1
	v_lshlrev_b32_e32 v5, 4, v166
	v_lshrrev_b32_e32 v0, 22, v0
	v_add_u32_e32 v0, v5, v0
	v_and_b32_e32 v0, 0xfffffc00, v0
	v_sub_u32_e32 v0, v5, v0
	v_lshrrev_b32_e32 v3, 4, v0
	v_bitop3_b32 v0, v3, v0, 32 bitop3:0x6c
	v_lshlrev_b32_e32 v3, 3, v2
	v_and_b32_e32 v4, -16, v3
	v_ashrrev_i32_e32 v3, 31, v0
	v_lshrrev_b32_e32 v3, 26, v3
	v_add_u32_e32 v6, v0, v3
	v_ashrrev_i32_e32 v3, 6, v6
	v_add_u32_e32 v7, v3, v4
	v_lshlrev_b32_e32 v4, 5, v2
	v_and_b32_e32 v8, 32, v4
	v_and_b32_e32 v4, 0xc0, v6
	v_sub_u32_e32 v0, v0, v4
	v_ashrrev_i16_sdwa v0, v203, sext(v0) dst_sel:DWORD dst_unused:UNUSED_PAD src0_sel:DWORD src1_sel:BYTE_0
	v_bfe_i32 v4, v0, 0, 16
	v_lshlrev_b32_e32 v0, 1, v7
	v_lshrrev_b32_e32 v6, 2, v7
	v_and_b32_e32 v9, 3, v3
	s_mov_b32 s13, 0xfffe0
	v_and_b32_e32 v0, 24, v0
	v_and_b32_e32 v6, 4, v6
	v_and_or_b32 v9, v7, s13, v9
	v_or3_b32 v0, v9, v6, v0
	v_add_lshl_u32 v6, v8, v4, 1
	v_lshl_add_u32 v130, v7, 12, v6
	v_lshl_add_u32 v0, v0, 12, v6
	v_add_u32_e32 v6, 0x2000, v5
	v_ashrrev_i32_e32 v5, 31, v6
	v_lshrrev_b32_e32 v5, 22, v5
	v_add_u32_e32 v5, v6, v5
	v_ashrrev_i32_e32 v5, 10, v5
	v_mul_i32_i24_e32 v7, 0x400, v5
	v_sub_u32_e32 v6, v6, v7
	v_lshrrev_b32_e32 v7, 4, v6
	v_bitop3_b32 v7, v7, v6, 32 bitop3:0x6c
	v_lshlrev_b32_e32 v6, 3, v5
	v_and_b32_e32 v8, -16, v6
	v_ashrrev_i32_e32 v6, 31, v7
	v_lshrrev_b32_e32 v6, 26, v6
	v_add_u32_e32 v9, v7, v6
	v_ashrrev_i32_e32 v6, 6, v9
	v_add_u32_e32 v8, v6, v8
	v_and_b32_e32 v12, 3, v6
	v_and_or_b32 v12, v8, s13, v12
	s_ashr_i32 s13, s52, 6
	s_ashr_i32 s12, s52, 8
	s_lshl_b32 s53, s13, 10
	v_and_b32_e32 v9, 0xc0, v9
	s_add_u32 s36, s24, s0
	v_sub_u32_e32 v7, v7, v9
	s_addc_u32 s40, s25, s1
	s_lshl_b64 s[0:1], s[38:39], 20
	v_lshlrev_b32_e32 v10, 5, v5
	v_ashrrev_i16_sdwa v7, v203, sext(v7) dst_sel:DWORD dst_unused:UNUSED_PAD src0_sel:DWORD src1_sel:BYTE_0
	v_lshlrev_b32_e32 v9, 1, v8
	v_lshrrev_b32_e32 v11, 2, v8
	s_add_u32 s48, s36, s0
	v_and_b32_e32 v10, 32, v10
	v_bfe_i32 v7, v7, 0, 16
	v_and_b32_e32 v9, 24, v9
	v_and_b32_e32 v11, 4, v11
	s_addc_u32 s49, s40, s1
	s_add_i32 s54, s53, 0
	v_or3_b32 v9, v12, v11, v9
	v_add_lshl_u32 v10, v10, v7, 1
	s_add_i32 m0, s54, 0x10000
	v_lshl_add_u32 v134, v9, 12, v10
	global_load_lds_dwordx4 v0, s[48:49]
	s_add_i32 m0, s54, 0x12000
	s_add_i32 s55, s54, 0x2000
	global_load_lds_dwordx4 v134, s[48:49]
	s_mov_b32 m0, s54
	v_lshl_add_u32 v132, v8, 12, v10
	global_load_lds_dwordx4 v130, s[46:47]
	s_mov_b32 m0, s55
	s_add_u32 s0, s48, 0x80000
	global_load_lds_dwordx4 v132, s[46:47]
	s_addc_u32 s1, s49, 0
	s_add_i32 m0, s54, 0x14000
	s_nop 0
	global_load_lds_dwordx4 v0, s[0:1]
	s_add_i32 m0, s54, 0x16000
	s_nop 0
	global_load_lds_dwordx4 v134, s[0:1]
	s_add_u32 s0, s46, 0x80000
	s_addc_u32 s1, s47, 0
	s_add_i32 s56, s54, 0x4000
	s_mov_b32 m0, s56
	s_add_i32 s57, s54, 0x6000
	global_load_lds_dwordx4 v130, s[0:1]
	s_mov_b32 m0, s57
	s_cmp_lg_u32 s12, 1
	global_load_lds_dwordx4 v132, s[0:1]
	s_cbranch_scc1 .LBB0_562
	s_barrier
	s_setprio 1

.LBB0_572:
	s_add_u32 s41, s46, 0xfff80080
	s_addc_u32 s48, s47, -1
	s_add_i32 s64, 0, 0x10000
	v_add_u32_e32 v156, s64, v141
	ds_read_b128 v[144:147], v156
	ds_read_b128 v[148:151], v156 offset:1024
	ds_read_b128 v[152:155], v156 offset:2048
	ds_read_b128 v[168:171], v156 offset:3072
	s_cmp_eq_u32 s39, 28
	s_cselect_b32 s51, s43, s48
	s_cselect_b32 s50, s42, s41
	s_cselect_b32 s49, s45, s13
	s_cselect_b32 s48, s44, s12
	v_lshl_add_u64 v[156:157], s[46:47], 0, v[136:137]
	s_add_i32 m0, s54, 0xc000
	ds_read_b128 v[172:175], v143
	ds_read_b128 v[176:179], v143 offset:1024
	ds_read_b128 v[180:183], v143 offset:2048
	ds_read_b128 v[184:187], v143 offset:3072
	ds_read_b128 v[188:191], v143 offset:4096
	ds_read_b128 v[192:195], v143 offset:5120
	ds_read_b128 v[196:199], v143 offset:6144
	ds_read_b128 v[224:227], v143 offset:7168
	global_load_lds_dwordx4 v[156:157], off
	v_lshl_add_u64 v[156:157], s[46:47], 0, v[138:139]
	s_add_i32 m0, s54, 0xe000
	s_nop 0
	global_load_lds_dwordx4 v[156:157], off
	s_waitcnt lgkmcnt(8)
	s_barrier
	s_waitcnt lgkmcnt(0)
	s_waitcnt lgkmcnt(0)
	v_mfma_f32_16x16x32_bf16 v[126:129], v[144:147], v[172:175], v[126:129]
	v_mfma_f32_16x16x32_bf16 v[122:125], v[152:155], v[172:175], v[122:125]
	v_mfma_f32_16x16x32_bf16 v[118:121], v[144:147], v[180:183], v[118:121]
	v_mfma_f32_16x16x32_bf16 v[114:117], v[152:155], v[180:183], v[114:117]
	v_mfma_f32_16x16x32_bf16 v[102:105], v[144:147], v[188:191], v[102:105]
	v_mfma_f32_16x16x32_bf16 v[98:101], v[152:155], v[188:191], v[98:101]
	v_mfma_f32_16x16x32_bf16 v[86:89], v[144:147], v[196:199], v[86:89]
	v_mfma_f32_16x16x32_bf16 v[82:85], v[152:155], v[196:199], v[82:85]
	v_mfma_f32_16x16x32_bf16 v[126:129], v[148:151], v[176:179], v[126:129]
	v_mfma_f32_16x16x32_bf16 v[122:125], v[168:171], v[176:179], v[122:125]
	v_mfma_f32_16x16x32_bf16 v[118:121], v[148:151], v[184:187], v[118:121]
	v_mfma_f32_16x16x32_bf16 v[114:117], v[168:171], v[184:187], v[114:117]
	v_mfma_f32_16x16x32_bf16 v[102:105], v[148:151], v[192:195], v[102:105]
	v_mfma_f32_16x16x32_bf16 v[98:101], v[168:171], v[192:195], v[98:101]
	v_mfma_f32_16x16x32_bf16 v[86:89], v[148:151], v[224:227], v[86:89]
	v_mfma_f32_16x16x32_bf16 v[82:85], v[168:171], v[224:227], v[82:85]
	s_barrier
	s_add_i32 s41, 0, 0x14000
	v_add_u32_e32 v156, s41, v141
	s_add_i32 s64, s64, s53
	ds_read_b128 v[228:231], v156
	ds_read_b128 v[232:235], v156 offset:1024
	ds_read_b128 v[236:239], v156 offset:2048
	ds_read_b128 v[240:243], v156 offset:3072
	v_lshl_add_u64 v[156:157], s[48:49], 0, v[0:1]
	s_mov_b32 m0, s64
	v_lshl_add_u64 v[200:201], s[48:49], 0, v[134:135]
	global_load_lds_dwordx4 v[156:157], off
	s_add_i32 m0, s64, 0x2000
	s_nop 0
	global_load_lds_dwordx4 v[200:201], off
	s_barrier
	s_waitcnt lgkmcnt(0)
	s_waitcnt lgkmcnt(0)
	v_mfma_f32_16x16x32_bf16 v[110:113], v[228:231], v[172:175], v[110:113]
	v_mfma_f32_16x16x32_bf16 v[106:109], v[236:239], v[172:175], v[106:109]
	v_mfma_f32_16x16x32_bf16 v[94:97], v[228:231], v[180:183], v[94:97]
	v_mfma_f32_16x16x32_bf16 v[90:93], v[236:239], v[180:183], v[90:93]
	v_mfma_f32_16x16x32_bf16 v[78:81], v[228:231], v[188:191], v[78:81]
	v_mfma_f32_16x16x32_bf16 v[74:77], v[236:239], v[188:191], v[74:77]
	v_mfma_f32_16x16x32_bf16 v[70:73], v[228:231], v[196:199], v[70:73]
	v_mfma_f32_16x16x32_bf16 v[66:69], v[236:239], v[196:199], v[66:69]
	v_mfma_f32_16x16x32_bf16 v[110:113], v[232:235], v[176:179], v[110:113]
	v_mfma_f32_16x16x32_bf16 v[106:109], v[240:243], v[176:179], v[106:109]
	v_mfma_f32_16x16x32_bf16 v[94:97], v[232:235], v[184:187], v[94:97]
	v_mfma_f32_16x16x32_bf16 v[90:93], v[240:243], v[184:187], v[90:93]
	v_mfma_f32_16x16x32_bf16 v[78:81], v[232:235], v[192:195], v[78:81]
	v_mfma_f32_16x16x32_bf16 v[74:77], v[240:243], v[192:195], v[74:77]
	v_mfma_f32_16x16x32_bf16 v[70:73], v[232:235], v[224:227], v[70:73]
	v_mfma_f32_16x16x32_bf16 v[66:69], v[240:243], v[224:227], v[66:69]
	s_mov_b32 m0, s54
	v_lshl_add_u64 v[210:211], s[50:51], 0, v[130:131]
	s_barrier
	ds_read_b128 v[172:175], v143 offset:16384
	ds_read_b128 v[176:179], v143 offset:17408
	ds_read_b128 v[180:183], v143 offset:18432
	ds_read_b128 v[184:187], v143 offset:19456
	ds_read_b128 v[188:191], v143 offset:20480
	ds_read_b128 v[192:195], v143 offset:21504
	ds_read_b128 v[196:199], v143 offset:22528
	ds_read_b128 v[224:227], v143 offset:23552
	global_load_lds_dwordx4 v[210:211], off
	v_lshl_add_u64 v[244:245], s[50:51], 0, v[132:133]
	s_mov_b32 m0, s55
	s_nop 0
	global_load_lds_dwordx4 v[244:245], off
	s_barrier
	s_waitcnt lgkmcnt(0)
	s_waitcnt lgkmcnt(0)
	v_mfma_f32_16x16x32_bf16 v[62:65], v[144:147], v[172:175], v[62:65]
	v_mfma_f32_16x16x32_bf16 v[58:61], v[152:155], v[172:175], v[58:61]
	v_mfma_f32_16x16x32_bf16 v[54:57], v[144:147], v[180:183], v[54:57]
	v_mfma_f32_16x16x32_bf16 v[50:53], v[152:155], v[180:183], v[50:53]
	v_mfma_f32_16x16x32_bf16 v[38:41], v[144:147], v[188:191], v[38:41]
	v_mfma_f32_16x16x32_bf16 v[34:37], v[152:155], v[188:191], v[34:37]
	v_mfma_f32_16x16x32_bf16 v[22:25], v[144:147], v[196:199], v[22:25]
	v_mfma_f32_16x16x32_bf16 v[18:21], v[152:155], v[196:199], v[18:21]
	v_mfma_f32_16x16x32_bf16 v[62:65], v[148:151], v[176:179], v[62:65]
	v_mfma_f32_16x16x32_bf16 v[58:61], v[168:171], v[176:179], v[58:61]
	v_mfma_f32_16x16x32_bf16 v[54:57], v[148:151], v[184:187], v[54:57]
	v_mfma_f32_16x16x32_bf16 v[50:53], v[168:171], v[184:187], v[50:53]
	v_mfma_f32_16x16x32_bf16 v[38:41], v[148:151], v[192:195], v[38:41]
	v_mfma_f32_16x16x32_bf16 v[34:37], v[168:171], v[192:195], v[34:37]
	v_mfma_f32_16x16x32_bf16 v[22:25], v[148:151], v[224:227], v[22:25]
	v_mfma_f32_16x16x32_bf16 v[18:21], v[168:171], v[224:227], v[18:21]
	s_barrier
	s_add_u32 s64, s48, 0x80000
	s_addc_u32 s65, s49, 0
	s_add_i32 s41, s41, s53
	v_lshl_add_u64 v[144:145], s[64:65], 0, v[0:1]
	s_mov_b32 m0, s41
	s_nop 0
	global_load_lds_dwordx4 v[144:145], off
	v_lshl_add_u64 v[144:145], s[64:65], 0, v[134:135]
	s_add_i32 m0, s41, 0x2000
	s_nop 0
	global_load_lds_dwordx4 v[144:145], off
	s_waitcnt vmcnt(6)
	s_barrier
	v_mfma_f32_16x16x32_bf16 v[46:49], v[228:231], v[172:175], v[46:49]
	v_mfma_f32_16x16x32_bf16 v[42:45], v[236:239], v[172:175], v[42:45]
	v_mfma_f32_16x16x32_bf16 v[30:33], v[228:231], v[180:183], v[30:33]
	v_mfma_f32_16x16x32_bf16 v[26:29], v[236:239], v[180:183], v[26:29]
	v_mfma_f32_16x16x32_bf16 v[14:17], v[228:231], v[188:191], v[14:17]
	v_mfma_f32_16x16x32_bf16 v[10:13], v[236:239], v[188:191], v[10:13]
	v_mfma_f32_16x16x32_bf16 v[6:9], v[228:231], v[196:199], v[6:9]
	v_mfma_f32_16x16x32_bf16 v[2:5], v[236:239], v[196:199], v[2:5]
	v_mfma_f32_16x16x32_bf16 v[46:49], v[232:235], v[176:179], v[46:49]
	v_mfma_f32_16x16x32_bf16 v[42:45], v[240:243], v[176:179], v[42:45]
	v_mfma_f32_16x16x32_bf16 v[30:33], v[232:235], v[184:187], v[30:33]
	v_mfma_f32_16x16x32_bf16 v[26:29], v[240:243], v[184:187], v[26:29]
	v_mfma_f32_16x16x32_bf16 v[14:17], v[232:235], v[192:195], v[14:17]
	v_mfma_f32_16x16x32_bf16 v[10:13], v[240:243], v[192:195], v[10:13]
	v_mfma_f32_16x16x32_bf16 v[6:9], v[232:235], v[224:227], v[6:9]
	v_mfma_f32_16x16x32_bf16 v[2:5], v[240:243], v[224:227], v[2:5]
	s_add_i32 s41, 0, 0x18000
	v_add_u32_e32 v161, s41, v141
	s_barrier
	ds_read_b128 v[144:147], v161
	ds_read_b128 v[148:151], v161 offset:1024
	ds_read_b128 v[152:155], v161 offset:2048
	ds_read_b128 v[168:171], v161 offset:3072
	s_add_u32 s50, s50, 0x80000
	s_addc_u32 s51, s51, 0
	s_mov_b32 m0, s56
	v_lshl_add_u64 v[228:229], s[50:51], 0, v[130:131]
	ds_read_b128 v[172:175], v143 offset:32768
	ds_read_b128 v[176:179], v143 offset:33792
	ds_read_b128 v[180:183], v143 offset:34816
	ds_read_b128 v[184:187], v143 offset:35840
	ds_read_b128 v[188:191], v143 offset:36864
	ds_read_b128 v[192:195], v143 offset:37888
	ds_read_b128 v[196:199], v143 offset:38912
	ds_read_b128 v[224:227], v143 offset:39936
	global_load_lds_dwordx4 v[228:229], off
	v_lshl_add_u64 v[228:229], s[50:51], 0, v[132:133]
	s_mov_b32 m0, s57
	s_nop 0
	global_load_lds_dwordx4 v[228:229], off
	s_waitcnt lgkmcnt(8)
	s_barrier
	s_waitcnt lgkmcnt(0)
	s_waitcnt lgkmcnt(0)
	v_mfma_f32_16x16x32_bf16 v[126:129], v[144:147], v[172:175], v[126:129]
	v_mfma_f32_16x16x32_bf16 v[122:125], v[152:155], v[172:175], v[122:125]
	v_mfma_f32_16x16x32_bf16 v[118:121], v[144:147], v[180:183], v[118:121]
	v_mfma_f32_16x16x32_bf16 v[114:117], v[152:155], v[180:183], v[114:117]
	v_mfma_f32_16x16x32_bf16 v[102:105], v[144:147], v[188:191], v[102:105]
	v_mfma_f32_16x16x32_bf16 v[98:101], v[152:155], v[188:191], v[98:101]
	v_mfma_f32_16x16x32_bf16 v[86:89], v[144:147], v[196:199], v[86:89]
	v_mfma_f32_16x16x32_bf16 v[82:85], v[152:155], v[196:199], v[82:85]
	v_mfma_f32_16x16x32_bf16 v[126:129], v[148:151], v[176:179], v[126:129]
	v_mfma_f32_16x16x32_bf16 v[122:125], v[168:171], v[176:179], v[122:125]
	v_mfma_f32_16x16x32_bf16 v[118:121], v[148:151], v[184:187], v[118:121]
	v_mfma_f32_16x16x32_bf16 v[114:117], v[168:171], v[184:187], v[114:117]
	v_mfma_f32_16x16x32_bf16 v[102:105], v[148:151], v[192:195], v[102:105]
	v_mfma_f32_16x16x32_bf16 v[98:101], v[168:171], v[192:195], v[98:101]
	v_mfma_f32_16x16x32_bf16 v[86:89], v[148:151], v[224:227], v[86:89]
	v_mfma_f32_16x16x32_bf16 v[82:85], v[168:171], v[224:227], v[82:85]
	s_barrier
	s_add_i32 s50, 0, 0x1c000
	s_add_i32 s41, s41, s53
	v_add_u32_e32 v161, s50, v141
	v_lshl_add_u64 v[156:157], v[156:157], 0, s[94:95]
	s_mov_b32 m0, s41
	ds_read_b128 v[228:231], v161
	ds_read_b128 v[232:235], v161 offset:1024
	ds_read_b128 v[236:239], v161 offset:2048
	ds_read_b128 v[240:243], v161 offset:3072
	global_load_lds_dwordx4 v[156:157], off
	v_lshl_add_u64 v[156:157], v[200:201], 0, s[94:95]
	s_add_i32 m0, s41, 0x2000
	s_nop 0
	global_load_lds_dwordx4 v[156:157], off
	s_barrier
	s_waitcnt lgkmcnt(0)
	s_waitcnt lgkmcnt(0)
	v_mfma_f32_16x16x32_bf16 v[110:113], v[228:231], v[172:175], v[110:113]
	v_mfma_f32_16x16x32_bf16 v[106:109], v[236:239], v[172:175], v[106:109]
	v_mfma_f32_16x16x32_bf16 v[94:97], v[228:231], v[180:183], v[94:97]
	v_mfma_f32_16x16x32_bf16 v[90:93], v[236:239], v[180:183], v[90:93]
	v_mfma_f32_16x16x32_bf16 v[78:81], v[228:231], v[188:191], v[78:81]
	v_mfma_f32_16x16x32_bf16 v[74:77], v[236:239], v[188:191], v[74:77]
	v_mfma_f32_16x16x32_bf16 v[70:73], v[228:231], v[196:199], v[70:73]
	v_mfma_f32_16x16x32_bf16 v[66:69], v[236:239], v[196:199], v[66:69]
	v_mfma_f32_16x16x32_bf16 v[110:113], v[232:235], v[176:179], v[110:113]
	v_mfma_f32_16x16x32_bf16 v[106:109], v[240:243], v[176:179], v[106:109]
	v_mfma_f32_16x16x32_bf16 v[94:97], v[232:235], v[184:187], v[94:97]
	v_mfma_f32_16x16x32_bf16 v[90:93], v[240:243], v[184:187], v[90:93]
	v_mfma_f32_16x16x32_bf16 v[78:81], v[232:235], v[192:195], v[78:81]
	v_mfma_f32_16x16x32_bf16 v[74:77], v[240:243], v[192:195], v[74:77]
	v_mfma_f32_16x16x32_bf16 v[70:73], v[232:235], v[224:227], v[70:73]
	v_mfma_f32_16x16x32_bf16 v[66:69], v[240:243], v[224:227], v[66:69]
	s_mov_b32 m0, s59
	v_lshl_add_u64 v[156:157], v[210:211], 0, s[94:95]
	s_barrier
	ds_read_b128 v[172:175], v143 offset:49152
	ds_read_b128 v[176:179], v143 offset:50176
	ds_read_b128 v[180:183], v143 offset:51200
	ds_read_b128 v[184:187], v143 offset:52224
	ds_read_b128 v[188:191], v143 offset:53248
	ds_read_b128 v[192:195], v143 offset:54272
	ds_read_b128 v[196:199], v143 offset:55296
	ds_read_b128 v[224:227], v143 offset:56320
	global_load_lds_dwordx4 v[156:157], off
	v_lshl_add_u64 v[156:157], v[244:245], 0, s[94:95]
	s_mov_b32 m0, s60
	s_nop 0
	global_load_lds_dwordx4 v[156:157], off
	s_barrier
	s_waitcnt lgkmcnt(0)
	s_waitcnt lgkmcnt(0)
	v_mfma_f32_16x16x32_bf16 v[62:65], v[144:147], v[172:175], v[62:65]
	v_mfma_f32_16x16x32_bf16 v[58:61], v[152:155], v[172:175], v[58:61]
	v_mfma_f32_16x16x32_bf16 v[54:57], v[144:147], v[180:183], v[54:57]
	v_mfma_f32_16x16x32_bf16 v[50:53], v[152:155], v[180:183], v[50:53]
	v_mfma_f32_16x16x32_bf16 v[38:41], v[144:147], v[188:191], v[38:41]
	v_mfma_f32_16x16x32_bf16 v[34:37], v[152:155], v[188:191], v[34:37]
	v_mfma_f32_16x16x32_bf16 v[22:25], v[144:147], v[196:199], v[22:25]
	v_mfma_f32_16x16x32_bf16 v[18:21], v[152:155], v[196:199], v[18:21]
	v_mfma_f32_16x16x32_bf16 v[62:65], v[148:151], v[176:179], v[62:65]
	v_mfma_f32_16x16x32_bf16 v[58:61], v[168:171], v[176:179], v[58:61]
	v_mfma_f32_16x16x32_bf16 v[54:57], v[148:151], v[184:187], v[54:57]
	v_mfma_f32_16x16x32_bf16 v[50:53], v[168:171], v[184:187], v[50:53]
	v_mfma_f32_16x16x32_bf16 v[38:41], v[148:151], v[192:195], v[38:41]
	v_mfma_f32_16x16x32_bf16 v[34:37], v[168:171], v[192:195], v[34:37]
	v_mfma_f32_16x16x32_bf16 v[22:25], v[148:151], v[224:227], v[22:25]
	v_mfma_f32_16x16x32_bf16 v[18:21], v[168:171], v[224:227], v[18:21]
	s_barrier
	s_add_u32 s48, s48, 0x80080
	s_addc_u32 s49, s49, 0
	s_add_i32 s41, s50, s53
	v_lshl_add_u64 v[144:145], s[48:49], 0, v[0:1]
	s_mov_b32 m0, s41
	s_nop 0
	global_load_lds_dwordx4 v[144:145], off
	v_lshl_add_u64 v[144:145], s[48:49], 0, v[134:135]
	s_add_i32 m0, s41, 0x2000
	s_nop 0
	global_load_lds_dwordx4 v[144:145], off
	s_waitcnt vmcnt(6)
	s_barrier
	v_mfma_f32_16x16x32_bf16 v[46:49], v[228:231], v[172:175], v[46:49]
	v_mfma_f32_16x16x32_bf16 v[42:45], v[236:239], v[172:175], v[42:45]
	v_mfma_f32_16x16x32_bf16 v[30:33], v[228:231], v[180:183], v[30:33]
	v_mfma_f32_16x16x32_bf16 v[26:29], v[236:239], v[180:183], v[26:29]
	v_mfma_f32_16x16x32_bf16 v[14:17], v[228:231], v[188:191], v[14:17]
	v_mfma_f32_16x16x32_bf16 v[10:13], v[236:239], v[188:191], v[10:13]
	v_mfma_f32_16x16x32_bf16 v[6:9], v[228:231], v[196:199], v[6:9]
	v_mfma_f32_16x16x32_bf16 v[2:5], v[236:239], v[196:199], v[2:5]
	v_mfma_f32_16x16x32_bf16 v[46:49], v[232:235], v[176:179], v[46:49]
	v_mfma_f32_16x16x32_bf16 v[42:45], v[240:243], v[176:179], v[42:45]
	v_mfma_f32_16x16x32_bf16 v[30:33], v[232:235], v[184:187], v[30:33]
	v_mfma_f32_16x16x32_bf16 v[26:29], v[240:243], v[184:187], v[26:29]
	v_mfma_f32_16x16x32_bf16 v[14:17], v[232:235], v[192:195], v[14:17]
	v_mfma_f32_16x16x32_bf16 v[10:13], v[240:243], v[192:195], v[10:13]
	v_mfma_f32_16x16x32_bf16 v[6:9], v[232:235], v[224:227], v[6:9]
	v_mfma_f32_16x16x32_bf16 v[2:5], v[240:243], v[224:227], v[2:5]
	s_add_i32 s39, s39, 2
	s_add_u32 s46, s46, 0x100
	s_addc_u32 s47, s47, 0
	s_add_u32 s12, s12, 0x100
	s_addc_u32 s13, s13, 0
	s_cmp_gt_u32 s39, 29
	s_barrier
	s_cbranch_scc0 .LBB0_572
	s_cmp_lg_u32 s62, 0
	s_cbranch_scc0 .LBB0_575
	s_lshl_b32 s39, s61, 8
	s_mov_b64 s[12:13], 0
	s_branch .LBB0_576

.LBB0_581:
	s_setprio 0
	v_readlane_b32 s60, v255, 21
	v_readlane_b32 s6, v255, 23
	s_mov_b32 s18, s60
	v_readlane_b32 s7, v255, 24
	v_readlane_b32 s56, v255, 29
	s_barrier
	v_readlane_b32 s61, v255, 22
	v_readlane_b32 s57, v255, 30

.LBB0_772:
	s_waitcnt lgkmcnt(0)
	v_ashrrev_i32_e32 v0, 31, v166
	v_lshrrev_b32_e32 v0, 26, v0
	v_add_u32_e32 v0, v166, v0
	s_waitcnt vmcnt(0)
	v_ashrrev_i32_e32 v2, 6, v0
	v_bfe_i32 v0, v166, 27, 1
	v_lshlrev_b32_e32 v5, 4, v166
	v_lshrrev_b32_e32 v0, 22, v0
	v_add_u32_e32 v0, v5, v0
	v_and_b32_e32 v0, 0xfffffc00, v0
	v_sub_u32_e32 v0, v5, v0
	v_lshrrev_b32_e32 v3, 4, v0
	v_bitop3_b32 v0, v3, v0, 32 bitop3:0x6c
	v_lshlrev_b32_e32 v3, 3, v2
	v_and_b32_e32 v4, -16, v3
	v_ashrrev_i32_e32 v3, 31, v0
	v_lshrrev_b32_e32 v3, 26, v3
	v_add_u32_e32 v6, v0, v3
	v_ashrrev_i32_e32 v3, 6, v6
	v_add_u32_e32 v7, v3, v4
	v_lshlrev_b32_e32 v4, 5, v2
	v_and_b32_e32 v8, 32, v4
	v_and_b32_e32 v4, 0xc0, v6
	v_sub_u32_e32 v0, v0, v4
	v_ashrrev_i16_sdwa v0, v203, sext(v0) dst_sel:DWORD dst_unused:UNUSED_PAD src0_sel:DWORD src1_sel:BYTE_0
	v_bfe_i32 v4, v0, 0, 16
	v_lshlrev_b32_e32 v0, 1, v7
	v_lshrrev_b32_e32 v6, 2, v7
	v_and_b32_e32 v9, 3, v3
	s_mov_b32 s13, 0xfffe0
	v_and_b32_e32 v0, 24, v0
	v_and_b32_e32 v6, 4, v6
	v_and_or_b32 v9, v7, s13, v9
	v_or3_b32 v0, v9, v6, v0
	v_add_lshl_u32 v6, v8, v4, 1
	v_lshl_add_u32 v130, v7, 12, v6
	v_lshl_add_u32 v0, v0, 12, v6
	v_add_u32_e32 v6, 0x2000, v5
	v_ashrrev_i32_e32 v5, 31, v6
	v_lshrrev_b32_e32 v5, 22, v5
	v_add_u32_e32 v5, v6, v5
	v_ashrrev_i32_e32 v5, 10, v5
	v_mul_i32_i24_e32 v7, 0x400, v5
	v_sub_u32_e32 v6, v6, v7
	v_lshrrev_b32_e32 v7, 4, v6
	v_bitop3_b32 v7, v7, v6, 32 bitop3:0x6c
	v_lshlrev_b32_e32 v6, 3, v5
	v_and_b32_e32 v8, -16, v6
	v_ashrrev_i32_e32 v6, 31, v7
	v_lshrrev_b32_e32 v6, 26, v6
	v_add_u32_e32 v9, v7, v6
	v_ashrrev_i32_e32 v6, 6, v9
	v_add_u32_e32 v8, v6, v8
	v_and_b32_e32 v12, 3, v6
	v_and_or_b32 v12, v8, s13, v12
	s_ashr_i32 s13, s52, 6
	s_ashr_i32 s12, s52, 8
	s_lshl_b32 s53, s13, 10
	v_and_b32_e32 v9, 0xc0, v9
	s_add_u32 s36, s24, s0
	v_sub_u32_e32 v7, v7, v9
	s_addc_u32 s40, s25, s1
	s_lshl_b64 s[0:1], s[38:39], 20
	v_lshlrev_b32_e32 v10, 5, v5
	v_ashrrev_i16_sdwa v7, v203, sext(v7) dst_sel:DWORD dst_unused:UNUSED_PAD src0_sel:DWORD src1_sel:BYTE_0
	v_lshlrev_b32_e32 v9, 1, v8
	v_lshrrev_b32_e32 v11, 2, v8
	s_add_u32 s48, s36, s0
	v_and_b32_e32 v10, 32, v10
	v_bfe_i32 v7, v7, 0, 16
	v_and_b32_e32 v9, 24, v9
	v_and_b32_e32 v11, 4, v11
	s_addc_u32 s49, s40, s1
	s_add_i32 s54, s53, 0
	v_or3_b32 v9, v12, v11, v9
	v_add_lshl_u32 v10, v10, v7, 1
	s_add_i32 m0, s54, 0x10000
	v_lshl_add_u32 v134, v9, 12, v10
	global_load_lds_dwordx4 v0, s[48:49]
	s_add_i32 m0, s54, 0x12000
	s_add_i32 s55, s54, 0x2000
	global_load_lds_dwordx4 v134, s[48:49]
	s_mov_b32 m0, s54
	v_lshl_add_u32 v132, v8, 12, v10
	global_load_lds_dwordx4 v130, s[46:47]
	s_mov_b32 m0, s55
	s_add_u32 s0, s48, 0x80000
	global_load_lds_dwordx4 v132, s[46:47]
	s_addc_u32 s1, s49, 0
	s_add_i32 m0, s54, 0x14000
	s_nop 0
	global_load_lds_dwordx4 v0, s[0:1]
	s_add_i32 m0, s54, 0x16000
	s_nop 0
	global_load_lds_dwordx4 v134, s[0:1]
	s_add_u32 s0, s46, 0x80000
	s_addc_u32 s1, s47, 0
	s_add_i32 s56, s54, 0x4000
	s_mov_b32 m0, s56
	s_add_i32 s57, s54, 0x6000
	global_load_lds_dwordx4 v130, s[0:1]
	s_mov_b32 m0, s57
	s_cmp_lg_u32 s12, 1
	global_load_lds_dwordx4 v132, s[0:1]
	s_cbranch_scc1 .LBB0_774
	s_barrier
	s_setprio 1

.LBB0_788:
	s_add_u32 s39, s46, 0xfff80080
	s_addc_u32 s48, s47, -1
	s_add_i32 s64, 0, 0x10000
	v_add_u32_e32 v156, s64, v141
	ds_read_b128 v[144:147], v156
	ds_read_b128 v[148:151], v156 offset:1024
	ds_read_b128 v[152:155], v156 offset:2048
	ds_read_b128 v[168:171], v156 offset:3072
	s_cmp_eq_u32 s13, 28
	s_cselect_b32 s51, s43, s48
	s_cselect_b32 s50, s42, s39
	s_cselect_b32 s49, s45, s12
	s_cselect_b32 s48, s44, s1
	v_lshl_add_u64 v[156:157], s[46:47], 0, v[136:137]
	s_add_i32 m0, s54, 0xc000
	ds_read_b128 v[172:175], v143
	ds_read_b128 v[176:179], v143 offset:1024
	ds_read_b128 v[180:183], v143 offset:2048
	ds_read_b128 v[184:187], v143 offset:3072
	ds_read_b128 v[188:191], v143 offset:4096
	ds_read_b128 v[192:195], v143 offset:5120
	ds_read_b128 v[196:199], v143 offset:6144
	ds_read_b128 v[224:227], v143 offset:7168
	global_load_lds_dwordx4 v[156:157], off
	v_lshl_add_u64 v[156:157], s[46:47], 0, v[138:139]
	s_add_i32 m0, s54, 0xe000
	s_nop 0
	global_load_lds_dwordx4 v[156:157], off
	s_waitcnt lgkmcnt(8)
	s_barrier
	s_waitcnt lgkmcnt(0)
	s_waitcnt lgkmcnt(0)
	v_mfma_f32_16x16x32_bf16 v[126:129], v[144:147], v[172:175], v[126:129]
	v_mfma_f32_16x16x32_bf16 v[122:125], v[152:155], v[172:175], v[122:125]
	v_mfma_f32_16x16x32_bf16 v[118:121], v[144:147], v[180:183], v[118:121]
	v_mfma_f32_16x16x32_bf16 v[114:117], v[152:155], v[180:183], v[114:117]
	v_mfma_f32_16x16x32_bf16 v[102:105], v[144:147], v[188:191], v[102:105]
	v_mfma_f32_16x16x32_bf16 v[98:101], v[152:155], v[188:191], v[98:101]
	v_mfma_f32_16x16x32_bf16 v[86:89], v[144:147], v[196:199], v[86:89]
	v_mfma_f32_16x16x32_bf16 v[82:85], v[152:155], v[196:199], v[82:85]
	v_mfma_f32_16x16x32_bf16 v[126:129], v[148:151], v[176:179], v[126:129]
	v_mfma_f32_16x16x32_bf16 v[122:125], v[168:171], v[176:179], v[122:125]
	v_mfma_f32_16x16x32_bf16 v[118:121], v[148:151], v[184:187], v[118:121]
	v_mfma_f32_16x16x32_bf16 v[114:117], v[168:171], v[184:187], v[114:117]
	v_mfma_f32_16x16x32_bf16 v[102:105], v[148:151], v[192:195], v[102:105]
	v_mfma_f32_16x16x32_bf16 v[98:101], v[168:171], v[192:195], v[98:101]
	v_mfma_f32_16x16x32_bf16 v[86:89], v[148:151], v[224:227], v[86:89]
	v_mfma_f32_16x16x32_bf16 v[82:85], v[168:171], v[224:227], v[82:85]
	s_barrier
	s_add_i32 s39, 0, 0x14000
	v_add_u32_e32 v156, s39, v141
	s_add_i32 s64, s64, s53
	ds_read_b128 v[228:231], v156
	ds_read_b128 v[232:235], v156 offset:1024
	ds_read_b128 v[236:239], v156 offset:2048
	ds_read_b128 v[240:243], v156 offset:3072
	v_lshl_add_u64 v[156:157], s[48:49], 0, v[0:1]
	s_mov_b32 m0, s64
	v_lshl_add_u64 v[200:201], s[48:49], 0, v[134:135]
	global_load_lds_dwordx4 v[156:157], off
	s_add_i32 m0, s64, 0x2000
	s_nop 0
	global_load_lds_dwordx4 v[200:201], off
	s_barrier
	s_waitcnt lgkmcnt(0)
	s_waitcnt lgkmcnt(0)
	v_mfma_f32_16x16x32_bf16 v[110:113], v[228:231], v[172:175], v[110:113]
	v_mfma_f32_16x16x32_bf16 v[106:109], v[236:239], v[172:175], v[106:109]
	v_mfma_f32_16x16x32_bf16 v[94:97], v[228:231], v[180:183], v[94:97]
	v_mfma_f32_16x16x32_bf16 v[90:93], v[236:239], v[180:183], v[90:93]
	v_mfma_f32_16x16x32_bf16 v[78:81], v[228:231], v[188:191], v[78:81]
	v_mfma_f32_16x16x32_bf16 v[74:77], v[236:239], v[188:191], v[74:77]
	v_mfma_f32_16x16x32_bf16 v[70:73], v[228:231], v[196:199], v[70:73]
	v_mfma_f32_16x16x32_bf16 v[66:69], v[236:239], v[196:199], v[66:69]
	v_mfma_f32_16x16x32_bf16 v[110:113], v[232:235], v[176:179], v[110:113]
	v_mfma_f32_16x16x32_bf16 v[106:109], v[240:243], v[176:179], v[106:109]
	v_mfma_f32_16x16x32_bf16 v[94:97], v[232:235], v[184:187], v[94:97]
	v_mfma_f32_16x16x32_bf16 v[90:93], v[240:243], v[184:187], v[90:93]
	v_mfma_f32_16x16x32_bf16 v[78:81], v[232:235], v[192:195], v[78:81]
	v_mfma_f32_16x16x32_bf16 v[74:77], v[240:243], v[192:195], v[74:77]
	v_mfma_f32_16x16x32_bf16 v[70:73], v[232:235], v[224:227], v[70:73]
	v_mfma_f32_16x16x32_bf16 v[66:69], v[240:243], v[224:227], v[66:69]
	s_mov_b32 m0, s54
	v_lshl_add_u64 v[210:211], s[50:51], 0, v[130:131]
	s_barrier
	ds_read_b128 v[172:175], v143 offset:16384
	ds_read_b128 v[176:179], v143 offset:17408
	ds_read_b128 v[180:183], v143 offset:18432
	ds_read_b128 v[184:187], v143 offset:19456
	ds_read_b128 v[188:191], v143 offset:20480
	ds_read_b128 v[192:195], v143 offset:21504
	ds_read_b128 v[196:199], v143 offset:22528
	ds_read_b128 v[224:227], v143 offset:23552
	global_load_lds_dwordx4 v[210:211], off
	v_lshl_add_u64 v[244:245], s[50:51], 0, v[132:133]
	s_mov_b32 m0, s55
	s_nop 0
	global_load_lds_dwordx4 v[244:245], off
	s_barrier
	s_waitcnt lgkmcnt(0)
	s_waitcnt lgkmcnt(0)
	v_mfma_f32_16x16x32_bf16 v[62:65], v[144:147], v[172:175], v[62:65]
	v_mfma_f32_16x16x32_bf16 v[58:61], v[152:155], v[172:175], v[58:61]
	v_mfma_f32_16x16x32_bf16 v[54:57], v[144:147], v[180:183], v[54:57]
	v_mfma_f32_16x16x32_bf16 v[50:53], v[152:155], v[180:183], v[50:53]
	v_mfma_f32_16x16x32_bf16 v[38:41], v[144:147], v[188:191], v[38:41]
	v_mfma_f32_16x16x32_bf16 v[34:37], v[152:155], v[188:191], v[34:37]
	v_mfma_f32_16x16x32_bf16 v[22:25], v[144:147], v[196:199], v[22:25]
	v_mfma_f32_16x16x32_bf16 v[18:21], v[152:155], v[196:199], v[18:21]
	v_mfma_f32_16x16x32_bf16 v[62:65], v[148:151], v[176:179], v[62:65]
	v_mfma_f32_16x16x32_bf16 v[58:61], v[168:171], v[176:179], v[58:61]
	v_mfma_f32_16x16x32_bf16 v[54:57], v[148:151], v[184:187], v[54:57]
	v_mfma_f32_16x16x32_bf16 v[50:53], v[168:171], v[184:187], v[50:53]
	v_mfma_f32_16x16x32_bf16 v[38:41], v[148:151], v[192:195], v[38:41]
	v_mfma_f32_16x16x32_bf16 v[34:37], v[168:171], v[192:195], v[34:37]
	v_mfma_f32_16x16x32_bf16 v[22:25], v[148:151], v[224:227], v[22:25]
	v_mfma_f32_16x16x32_bf16 v[18:21], v[168:171], v[224:227], v[18:21]
	s_barrier
	s_add_u32 s64, s48, 0x80000
	s_addc_u32 s65, s49, 0
	s_add_i32 s39, s39, s53
	v_lshl_add_u64 v[144:145], s[64:65], 0, v[0:1]
	s_mov_b32 m0, s39
	s_nop 0
	global_load_lds_dwordx4 v[144:145], off
	v_lshl_add_u64 v[144:145], s[64:65], 0, v[134:135]
	s_add_i32 m0, s39, 0x2000
	s_nop 0
	global_load_lds_dwordx4 v[144:145], off
	s_waitcnt vmcnt(6)
	s_barrier
	v_mfma_f32_16x16x32_bf16 v[46:49], v[228:231], v[172:175], v[46:49]
	v_mfma_f32_16x16x32_bf16 v[42:45], v[236:239], v[172:175], v[42:45]
	v_mfma_f32_16x16x32_bf16 v[30:33], v[228:231], v[180:183], v[30:33]
	v_mfma_f32_16x16x32_bf16 v[26:29], v[236:239], v[180:183], v[26:29]
	v_mfma_f32_16x16x32_bf16 v[14:17], v[228:231], v[188:191], v[14:17]
	v_mfma_f32_16x16x32_bf16 v[10:13], v[236:239], v[188:191], v[10:13]
	v_mfma_f32_16x16x32_bf16 v[6:9], v[228:231], v[196:199], v[6:9]
	v_mfma_f32_16x16x32_bf16 v[2:5], v[236:239], v[196:199], v[2:5]
	v_mfma_f32_16x16x32_bf16 v[46:49], v[232:235], v[176:179], v[46:49]
	v_mfma_f32_16x16x32_bf16 v[42:45], v[240:243], v[176:179], v[42:45]
	v_mfma_f32_16x16x32_bf16 v[30:33], v[232:235], v[184:187], v[30:33]
	v_mfma_f32_16x16x32_bf16 v[26:29], v[240:243], v[184:187], v[26:29]
	v_mfma_f32_16x16x32_bf16 v[14:17], v[232:235], v[192:195], v[14:17]
	v_mfma_f32_16x16x32_bf16 v[10:13], v[240:243], v[192:195], v[10:13]
	v_mfma_f32_16x16x32_bf16 v[6:9], v[232:235], v[224:227], v[6:9]
	v_mfma_f32_16x16x32_bf16 v[2:5], v[240:243], v[224:227], v[2:5]
	s_add_i32 s39, 0, 0x18000
	v_add_u32_e32 v161, s39, v141
	s_barrier
	ds_read_b128 v[144:147], v161
	ds_read_b128 v[148:151], v161 offset:1024
	ds_read_b128 v[152:155], v161 offset:2048
	ds_read_b128 v[168:171], v161 offset:3072
	s_add_u32 s50, s50, 0x80000
	s_addc_u32 s51, s51, 0
	s_mov_b32 m0, s56
	v_lshl_add_u64 v[228:229], s[50:51], 0, v[130:131]
	ds_read_b128 v[172:175], v143 offset:32768
	ds_read_b128 v[176:179], v143 offset:33792
	ds_read_b128 v[180:183], v143 offset:34816
	ds_read_b128 v[184:187], v143 offset:35840
	ds_read_b128 v[188:191], v143 offset:36864
	ds_read_b128 v[192:195], v143 offset:37888
	ds_read_b128 v[196:199], v143 offset:38912
	ds_read_b128 v[224:227], v143 offset:39936
	global_load_lds_dwordx4 v[228:229], off
	v_lshl_add_u64 v[228:229], s[50:51], 0, v[132:133]
	s_mov_b32 m0, s57
	s_nop 0
	global_load_lds_dwordx4 v[228:229], off
	s_waitcnt lgkmcnt(8)
	s_barrier
	s_waitcnt lgkmcnt(0)
	s_waitcnt lgkmcnt(0)
	v_mfma_f32_16x16x32_bf16 v[126:129], v[144:147], v[172:175], v[126:129]
	v_mfma_f32_16x16x32_bf16 v[122:125], v[152:155], v[172:175], v[122:125]
	v_mfma_f32_16x16x32_bf16 v[118:121], v[144:147], v[180:183], v[118:121]
	v_mfma_f32_16x16x32_bf16 v[114:117], v[152:155], v[180:183], v[114:117]
	v_mfma_f32_16x16x32_bf16 v[102:105], v[144:147], v[188:191], v[102:105]
	v_mfma_f32_16x16x32_bf16 v[98:101], v[152:155], v[188:191], v[98:101]
	v_mfma_f32_16x16x32_bf16 v[86:89], v[144:147], v[196:199], v[86:89]
	v_mfma_f32_16x16x32_bf16 v[82:85], v[152:155], v[196:199], v[82:85]
	v_mfma_f32_16x16x32_bf16 v[126:129], v[148:151], v[176:179], v[126:129]
	v_mfma_f32_16x16x32_bf16 v[122:125], v[168:171], v[176:179], v[122:125]
	v_mfma_f32_16x16x32_bf16 v[118:121], v[148:151], v[184:187], v[118:121]
	v_mfma_f32_16x16x32_bf16 v[114:117], v[168:171], v[184:187], v[114:117]
	v_mfma_f32_16x16x32_bf16 v[102:105], v[148:151], v[192:195], v[102:105]
	v_mfma_f32_16x16x32_bf16 v[98:101], v[168:171], v[192:195], v[98:101]
	v_mfma_f32_16x16x32_bf16 v[86:89], v[148:151], v[224:227], v[86:89]
	v_mfma_f32_16x16x32_bf16 v[82:85], v[168:171], v[224:227], v[82:85]
	s_barrier
	s_add_i32 s50, 0, 0x1c000
	s_add_i32 s39, s39, s53
	v_add_u32_e32 v161, s50, v141
	v_lshl_add_u64 v[156:157], v[156:157], 0, s[94:95]
	s_mov_b32 m0, s39
	ds_read_b128 v[228:231], v161
	ds_read_b128 v[232:235], v161 offset:1024
	ds_read_b128 v[236:239], v161 offset:2048
	ds_read_b128 v[240:243], v161 offset:3072
	global_load_lds_dwordx4 v[156:157], off
	v_lshl_add_u64 v[156:157], v[200:201], 0, s[94:95]
	s_add_i32 m0, s39, 0x2000
	s_nop 0
	global_load_lds_dwordx4 v[156:157], off
	s_barrier
	s_waitcnt lgkmcnt(0)
	s_waitcnt lgkmcnt(0)
	v_mfma_f32_16x16x32_bf16 v[110:113], v[228:231], v[172:175], v[110:113]
	v_mfma_f32_16x16x32_bf16 v[106:109], v[236:239], v[172:175], v[106:109]
	v_mfma_f32_16x16x32_bf16 v[94:97], v[228:231], v[180:183], v[94:97]
	v_mfma_f32_16x16x32_bf16 v[90:93], v[236:239], v[180:183], v[90:93]
	v_mfma_f32_16x16x32_bf16 v[78:81], v[228:231], v[188:191], v[78:81]
	v_mfma_f32_16x16x32_bf16 v[74:77], v[236:239], v[188:191], v[74:77]
	v_mfma_f32_16x16x32_bf16 v[70:73], v[228:231], v[196:199], v[70:73]
	v_mfma_f32_16x16x32_bf16 v[66:69], v[236:239], v[196:199], v[66:69]
	v_mfma_f32_16x16x32_bf16 v[110:113], v[232:235], v[176:179], v[110:113]
	v_mfma_f32_16x16x32_bf16 v[106:109], v[240:243], v[176:179], v[106:109]
	v_mfma_f32_16x16x32_bf16 v[94:97], v[232:235], v[184:187], v[94:97]
	v_mfma_f32_16x16x32_bf16 v[90:93], v[240:243], v[184:187], v[90:93]
	v_mfma_f32_16x16x32_bf16 v[78:81], v[232:235], v[192:195], v[78:81]
	v_mfma_f32_16x16x32_bf16 v[74:77], v[240:243], v[192:195], v[74:77]
	v_mfma_f32_16x16x32_bf16 v[70:73], v[232:235], v[224:227], v[70:73]
	v_mfma_f32_16x16x32_bf16 v[66:69], v[240:243], v[224:227], v[66:69]
	s_mov_b32 m0, s59
	v_lshl_add_u64 v[156:157], v[210:211], 0, s[94:95]
	s_barrier
	ds_read_b128 v[172:175], v143 offset:49152
	ds_read_b128 v[176:179], v143 offset:50176
	ds_read_b128 v[180:183], v143 offset:51200
	ds_read_b128 v[184:187], v143 offset:52224
	ds_read_b128 v[188:191], v143 offset:53248
	ds_read_b128 v[192:195], v143 offset:54272
	ds_read_b128 v[196:199], v143 offset:55296
	ds_read_b128 v[224:227], v143 offset:56320
	global_load_lds_dwordx4 v[156:157], off
	v_lshl_add_u64 v[156:157], v[244:245], 0, s[94:95]
	s_mov_b32 m0, s61
	s_nop 0
	global_load_lds_dwordx4 v[156:157], off
	s_barrier
	s_waitcnt lgkmcnt(0)
	s_waitcnt lgkmcnt(0)
	v_mfma_f32_16x16x32_bf16 v[62:65], v[144:147], v[172:175], v[62:65]
	v_mfma_f32_16x16x32_bf16 v[58:61], v[152:155], v[172:175], v[58:61]
	v_mfma_f32_16x16x32_bf16 v[54:57], v[144:147], v[180:183], v[54:57]
	v_mfma_f32_16x16x32_bf16 v[50:53], v[152:155], v[180:183], v[50:53]
	v_mfma_f32_16x16x32_bf16 v[38:41], v[144:147], v[188:191], v[38:41]
	v_mfma_f32_16x16x32_bf16 v[34:37], v[152:155], v[188:191], v[34:37]
	v_mfma_f32_16x16x32_bf16 v[22:25], v[144:147], v[196:199], v[22:25]
	v_mfma_f32_16x16x32_bf16 v[18:21], v[152:155], v[196:199], v[18:21]
	v_mfma_f32_16x16x32_bf16 v[62:65], v[148:151], v[176:179], v[62:65]
	v_mfma_f32_16x16x32_bf16 v[58:61], v[168:171], v[176:179], v[58:61]
	v_mfma_f32_16x16x32_bf16 v[54:57], v[148:151], v[184:187], v[54:57]
	v_mfma_f32_16x16x32_bf16 v[50:53], v[168:171], v[184:187], v[50:53]
	v_mfma_f32_16x16x32_bf16 v[38:41], v[148:151], v[192:195], v[38:41]
	v_mfma_f32_16x16x32_bf16 v[34:37], v[168:171], v[192:195], v[34:37]
	v_mfma_f32_16x16x32_bf16 v[22:25], v[148:151], v[224:227], v[22:25]
	v_mfma_f32_16x16x32_bf16 v[18:21], v[168:171], v[224:227], v[18:21]
	s_barrier
	s_add_u32 s48, s48, 0x80080
	s_addc_u32 s49, s49, 0
	s_add_i32 s39, s50, s53
	v_lshl_add_u64 v[144:145], s[48:49], 0, v[0:1]
	s_mov_b32 m0, s39
	s_nop 0
	global_load_lds_dwordx4 v[144:145], off
	v_lshl_add_u64 v[144:145], s[48:49], 0, v[134:135]
	s_add_i32 m0, s39, 0x2000
	s_nop 0
	global_load_lds_dwordx4 v[144:145], off
	s_waitcnt vmcnt(6)
	s_barrier
	v_mfma_f32_16x16x32_bf16 v[46:49], v[228:231], v[172:175], v[46:49]
	v_mfma_f32_16x16x32_bf16 v[42:45], v[236:239], v[172:175], v[42:45]
	v_mfma_f32_16x16x32_bf16 v[30:33], v[228:231], v[180:183], v[30:33]
	v_mfma_f32_16x16x32_bf16 v[26:29], v[236:239], v[180:183], v[26:29]
	v_mfma_f32_16x16x32_bf16 v[14:17], v[228:231], v[188:191], v[14:17]
	v_mfma_f32_16x16x32_bf16 v[10:13], v[236:239], v[188:191], v[10:13]
	v_mfma_f32_16x16x32_bf16 v[6:9], v[228:231], v[196:199], v[6:9]
	v_mfma_f32_16x16x32_bf16 v[2:5], v[236:239], v[196:199], v[2:5]
	v_mfma_f32_16x16x32_bf16 v[46:49], v[232:235], v[176:179], v[46:49]
	v_mfma_f32_16x16x32_bf16 v[42:45], v[240:243], v[176:179], v[42:45]
	v_mfma_f32_16x16x32_bf16 v[30:33], v[232:235], v[184:187], v[30:33]
	v_mfma_f32_16x16x32_bf16 v[26:29], v[240:243], v[184:187], v[26:29]
	v_mfma_f32_16x16x32_bf16 v[14:17], v[232:235], v[192:195], v[14:17]
	v_mfma_f32_16x16x32_bf16 v[10:13], v[240:243], v[192:195], v[10:13]
	v_mfma_f32_16x16x32_bf16 v[6:9], v[232:235], v[224:227], v[6:9]
	v_mfma_f32_16x16x32_bf16 v[2:5], v[240:243], v[224:227], v[2:5]
	s_add_i32 s13, s13, 2
	s_add_u32 s46, s46, 0x100
	s_addc_u32 s47, s47, 0
	s_add_u32 s1, s1, 0x100
	s_addc_u32 s12, s12, 0
	s_cmp_gt_u32 s13, 29
	s_barrier
	s_cbranch_scc0 .LBB0_788
	s_cmp_lg_u32 s62, 0
	s_cbranch_scc0 .LBB0_791
	s_lshl_b32 s1, s60, 8
	s_mov_b64 s[12:13], 0
	s_branch .LBB0_792

.LBB0_887:
	s_setprio 0
	s_add_i32 s26, s26, 1
	s_cmp_ge_i32 s26, s27
	s_mov_b64 s[0:1], -1
	v_readlane_b32 s64, v255, 31
	v_readlane_b32 s66, v255, 33
	v_readlane_b32 s58, v255, 35
	v_readlane_b32 s78, v255, 37
	v_readlane_b32 s65, v255, 32
	v_readlane_b32 s67, v255, 34
	v_readlane_b32 s59, v255, 36
	v_readlane_b32 s79, v255, 38
	s_cbranch_scc1 .Ltr_9
	v_readlane_b32 s0, v251, 39
	v_readlane_b32 s1, v251, 40
	s_andn2_b64 vcc, exec, s[0:1]
	s_cbranch_vccnz .LBB0_900
	s_waitcnt vmcnt(0) lgkmcnt(0)
	s_barrier
	s_mov_b64 s[0:1], exec
	v_readlane_b32 s12, v254, 43
	v_readlane_b32 s13, v254, 44
	s_and_b64 s[12:13], s[0:1], s[12:13]
	s_mov_b64 exec, s[12:13]
	s_cbranch_execz .LBB0_899
	v_readlane_b32 s38, v250, 0
	v_readlane_b32 s39, v250, 1
	buffer_wbl2 sc1
	s_load_dwordx2 s[38:39], s[38:39], 0x58
	s_mov_b64 s[12:13], exec
	v_mbcnt_lo_u32_b32 v2, s12, 0
	v_mbcnt_hi_u32_b32 v2, s13, v2
	v_cmp_eq_u32_e32 vcc, 0, v2
	s_waitcnt lgkmcnt(0)
	global_load_dword v0, v1, s[38:39] offset:40
	s_and_saveexec_b64 s[40:41], vcc
	s_cbranch_execz .LBB0_892
	s_bcnt1_i32_b64 s12, s[12:13]
	v_mov_b32_e32 v3, s12
	global_atomic_add v3, v1, v3, s[38:39] offset:32 sc0
